# v63 + loop-edge rotation: loop-control SALU moved in front of the loop-back barrier in every GEMM K-loop
# baseline (speedup 1.0000x reference)
.LBB0_412:
	ds_read_b128 v[130:133], v191
	ds_read_b128 v[134:137], v191 offset:1024
	ds_read_b128 v[138:141], v191 offset:2048
	ds_read_b128 v[142:145], v191 offset:3072
	ds_read_b128 v[146:149], v192
	ds_read_b128 v[150:153], v192 offset:1024
	ds_read_b128 v[174:177], v192 offset:2048
	s_waitcnt lgkmcnt(0)
	ds_read_b128 v[178:181], v192 offset:3072
	s_add_u32 s42, s40, 0xfff00080
	s_addc_u32 s43, s41, -1
	s_cmp_eq_u32 s29, 60
	s_cselect_b32 s45, s0, s43
	s_cselect_b32 s44, s1, s42
	s_cselect_b32 s43, s7, s27
	s_cselect_b32 s42, s14, s15
	v_lshl_add_u64 v[186:187], s[40:41], 0, v[170:171]
	s_add_i32 m0, s9, 0xc000
	ds_read_b128 v[182:185], v193
	ds_read_b128 v[204:207], v193 offset:1024
	ds_read_b128 v[208:211], v193 offset:2048
	ds_read_b128 v[212:215], v193 offset:3072
	ds_read_b128 v[216:219], v193 offset:4096
	ds_read_b128 v[220:223], v193 offset:5120
	ds_read_b128 v[224:227], v193 offset:6144
	ds_read_b128 v[234:237], v193 offset:7168
	global_load_lds_dwordx4 v[186:187], off
	v_lshl_add_u64 v[186:187], s[40:41], 0, v[172:173]
	s_add_i32 m0, s9, 0xe000
	s_nop 0
	global_load_lds_dwordx4 v[186:187], off
	s_waitcnt vmcnt(8)
	s_waitcnt lgkmcnt(0)
	s_barrier
	s_waitcnt lgkmcnt(0)
	v_mfma_f32_16x16x32_bf16 v[126:129], v[130:133], v[182:185], v[126:129]
	v_mfma_f32_16x16x32_bf16 v[122:125], v[138:141], v[182:185], v[122:125]
	v_mfma_f32_16x16x32_bf16 v[118:121], v[130:133], v[208:211], v[118:121]
	v_mfma_f32_16x16x32_bf16 v[110:113], v[138:141], v[208:211], v[110:113]
	v_mfma_f32_16x16x32_bf16 v[102:105], v[130:133], v[216:219], v[102:105]
	v_mfma_f32_16x16x32_bf16 v[94:97], v[138:141], v[216:219], v[94:97]
	v_mfma_f32_16x16x32_bf16 v[86:89], v[130:133], v[224:227], v[86:89]
	v_mfma_f32_16x16x32_bf16 v[78:81], v[138:141], v[224:227], v[78:81]
	v_mfma_f32_16x16x32_bf16 v[126:129], v[134:137], v[204:207], v[126:129]
	v_mfma_f32_16x16x32_bf16 v[122:125], v[142:145], v[204:207], v[122:125]
	v_mfma_f32_16x16x32_bf16 v[118:121], v[134:137], v[212:215], v[118:121]
	v_mfma_f32_16x16x32_bf16 v[110:113], v[142:145], v[212:215], v[110:113]
	v_mfma_f32_16x16x32_bf16 v[102:105], v[134:137], v[220:223], v[102:105]
	v_mfma_f32_16x16x32_bf16 v[94:97], v[142:145], v[220:223], v[94:97]
	v_mfma_f32_16x16x32_bf16 v[86:89], v[134:137], v[234:237], v[86:89]
	v_mfma_f32_16x16x32_bf16 v[78:81], v[142:145], v[234:237], v[78:81]
	v_mfma_f32_16x16x32_bf16 v[114:117], v[146:149], v[182:185], v[114:117]
	v_mfma_f32_16x16x32_bf16 v[106:109], v[174:177], v[182:185], v[106:109]
	v_mfma_f32_16x16x32_bf16 v[98:101], v[146:149], v[208:211], v[98:101]
	v_mfma_f32_16x16x32_bf16 v[90:93], v[174:177], v[208:211], v[90:93]
	v_mfma_f32_16x16x32_bf16 v[82:85], v[146:149], v[216:219], v[82:85]
	v_mfma_f32_16x16x32_bf16 v[74:77], v[174:177], v[216:219], v[74:77]
	v_mfma_f32_16x16x32_bf16 v[70:73], v[146:149], v[224:227], v[70:73]
	v_mfma_f32_16x16x32_bf16 v[66:69], v[174:177], v[224:227], v[66:69]
	v_mfma_f32_16x16x32_bf16 v[114:117], v[150:153], v[204:207], v[114:117]
	v_mfma_f32_16x16x32_bf16 v[106:109], v[178:181], v[204:207], v[106:109]
	v_mfma_f32_16x16x32_bf16 v[98:101], v[150:153], v[212:215], v[98:101]
	v_mfma_f32_16x16x32_bf16 v[90:93], v[178:181], v[212:215], v[90:93]
	v_mfma_f32_16x16x32_bf16 v[82:85], v[150:153], v[220:223], v[82:85]
	v_mfma_f32_16x16x32_bf16 v[74:77], v[178:181], v[220:223], v[74:77]
	v_mfma_f32_16x16x32_bf16 v[70:73], v[150:153], v[234:237], v[70:73]
	v_mfma_f32_16x16x32_bf16 v[66:69], v[178:181], v[234:237], v[66:69]
	s_barrier
	s_add_i32 s46, s52, s8
	v_lshl_add_u64 v[186:187], s[42:43], 0, v[158:159]
	s_mov_b32 m0, s46
	ds_read_b128 v[182:185], v193 offset:16384
	ds_read_b128 v[204:207], v193 offset:17408
	ds_read_b128 v[208:211], v193 offset:18432
	ds_read_b128 v[212:215], v193 offset:19456
	ds_read_b128 v[216:219], v193 offset:20480
	ds_read_b128 v[220:223], v193 offset:21504
	ds_read_b128 v[224:227], v193 offset:22528
	ds_read_b128 v[234:237], v193 offset:23552
	global_load_lds_dwordx4 v[186:187], off
	s_add_i32 m0, s46, 0x2000
	s_add_u32 s46, s42, 0x100000
	v_lshl_add_u64 v[194:195], s[42:43], 0, v[162:163]
	s_addc_u32 s47, s43, 0
	s_add_i32 s56, s53, s8
	global_load_lds_dwordx4 v[194:195], off
	v_lshl_add_u64 v[200:201], s[46:47], 0, v[158:159]
	s_mov_b32 m0, s56
	v_lshl_add_u64 v[238:239], s[44:45], 0, v[160:161]
	global_load_lds_dwordx4 v[200:201], off
	v_lshl_add_u64 v[200:201], s[46:47], 0, v[162:163]
	s_add_i32 m0, s56, 0x2000
	s_nop 0
	global_load_lds_dwordx4 v[200:201], off
	v_lshl_add_u64 v[200:201], s[44:45], 0, v[156:157]
	s_mov_b32 m0, s9
	s_nop 0
	global_load_lds_dwordx4 v[200:201], off
	s_mov_b32 m0, s13
	s_nop 0
	global_load_lds_dwordx4 v[238:239], off
	s_waitcnt vmcnt(8)
	s_waitcnt lgkmcnt(0)
	s_barrier
	s_waitcnt lgkmcnt(0)
	v_mfma_f32_16x16x32_bf16 v[62:65], v[130:133], v[182:185], v[62:65]
	v_mfma_f32_16x16x32_bf16 v[58:61], v[138:141], v[182:185], v[58:61]
	v_mfma_f32_16x16x32_bf16 v[54:57], v[130:133], v[208:211], v[54:57]
	v_mfma_f32_16x16x32_bf16 v[46:49], v[138:141], v[208:211], v[46:49]
	v_mfma_f32_16x16x32_bf16 v[38:41], v[130:133], v[216:219], v[38:41]
	v_mfma_f32_16x16x32_bf16 v[30:33], v[138:141], v[216:219], v[30:33]
	v_mfma_f32_16x16x32_bf16 v[22:25], v[130:133], v[224:227], v[22:25]
	v_mfma_f32_16x16x32_bf16 v[14:17], v[138:141], v[224:227], v[14:17]
	v_mfma_f32_16x16x32_bf16 v[62:65], v[134:137], v[204:207], v[62:65]
	v_mfma_f32_16x16x32_bf16 v[58:61], v[142:145], v[204:207], v[58:61]
	v_mfma_f32_16x16x32_bf16 v[54:57], v[134:137], v[212:215], v[54:57]
	v_mfma_f32_16x16x32_bf16 v[46:49], v[142:145], v[212:215], v[46:49]
	v_mfma_f32_16x16x32_bf16 v[38:41], v[134:137], v[220:223], v[38:41]
	v_mfma_f32_16x16x32_bf16 v[30:33], v[142:145], v[220:223], v[30:33]
	v_mfma_f32_16x16x32_bf16 v[22:25], v[134:137], v[234:237], v[22:25]
	v_mfma_f32_16x16x32_bf16 v[14:17], v[142:145], v[234:237], v[14:17]
	v_mfma_f32_16x16x32_bf16 v[50:53], v[146:149], v[182:185], v[50:53]
	v_mfma_f32_16x16x32_bf16 v[42:45], v[174:177], v[182:185], v[42:45]
	v_mfma_f32_16x16x32_bf16 v[34:37], v[146:149], v[208:211], v[34:37]
	v_mfma_f32_16x16x32_bf16 v[26:29], v[174:177], v[208:211], v[26:29]
	v_mfma_f32_16x16x32_bf16 v[18:21], v[146:149], v[216:219], v[18:21]
	v_mfma_f32_16x16x32_bf16 v[10:13], v[174:177], v[216:219], v[10:13]
	v_mfma_f32_16x16x32_bf16 v[6:9], v[146:149], v[224:227], v[6:9]
	v_mfma_f32_16x16x32_bf16 v[2:5], v[174:177], v[224:227], v[2:5]
	v_mfma_f32_16x16x32_bf16 v[50:53], v[150:153], v[204:207], v[50:53]
	v_mfma_f32_16x16x32_bf16 v[42:45], v[178:181], v[204:207], v[42:45]
	v_mfma_f32_16x16x32_bf16 v[34:37], v[150:153], v[212:215], v[34:37]
	v_mfma_f32_16x16x32_bf16 v[26:29], v[178:181], v[212:215], v[26:29]
	v_mfma_f32_16x16x32_bf16 v[18:21], v[150:153], v[220:223], v[18:21]
	v_mfma_f32_16x16x32_bf16 v[10:13], v[178:181], v[220:223], v[10:13]
	v_mfma_f32_16x16x32_bf16 v[6:9], v[150:153], v[234:237], v[6:9]
	v_mfma_f32_16x16x32_bf16 v[2:5], v[178:181], v[234:237], v[2:5]
	s_barrier
	s_add_i32 s46, 0, 0x18000
	s_add_i32 s47, 0, 0x1c000
	v_add_u32_e32 v142, s46, v188
	v_add_u32_e32 v164, s47, v188
	ds_read_b128 v[130:133], v142
	ds_read_b128 v[134:137], v142 offset:1024
	ds_read_b128 v[138:141], v142 offset:2048
	ds_read_b128 v[142:145], v142 offset:3072
	ds_read_b128 v[146:149], v164
	ds_read_b128 v[150:153], v164 offset:1024
	ds_read_b128 v[174:177], v164 offset:2048
	ds_read_b128 v[178:181], v164 offset:3072
	s_add_u32 s44, s44, 0x100000
	s_addc_u32 s45, s45, 0
	s_mov_b32 m0, s33
	v_lshl_add_u64 v[240:241], s[44:45], 0, v[156:157]
	ds_read_b128 v[182:185], v193 offset:32768
	ds_read_b128 v[204:207], v193 offset:33792
	ds_read_b128 v[208:211], v193 offset:34816
	ds_read_b128 v[212:215], v193 offset:35840
	ds_read_b128 v[216:219], v193 offset:36864
	ds_read_b128 v[220:223], v193 offset:37888
	ds_read_b128 v[224:227], v193 offset:38912
	ds_read_b128 v[234:237], v193 offset:39936
	global_load_lds_dwordx4 v[240:241], off
	v_lshl_add_u64 v[240:241], s[44:45], 0, v[160:161]
	s_mov_b32 m0, s39
	s_nop 0
	global_load_lds_dwordx4 v[240:241], off
	s_waitcnt vmcnt(8)
	s_waitcnt lgkmcnt(0)
	s_barrier
	s_waitcnt lgkmcnt(0)
	v_mfma_f32_16x16x32_bf16 v[126:129], v[130:133], v[182:185], v[126:129]
	v_mfma_f32_16x16x32_bf16 v[122:125], v[138:141], v[182:185], v[122:125]
	v_mfma_f32_16x16x32_bf16 v[118:121], v[130:133], v[208:211], v[118:121]
	v_mfma_f32_16x16x32_bf16 v[110:113], v[138:141], v[208:211], v[110:113]
	v_mfma_f32_16x16x32_bf16 v[102:105], v[130:133], v[216:219], v[102:105]
	v_mfma_f32_16x16x32_bf16 v[94:97], v[138:141], v[216:219], v[94:97]
	v_mfma_f32_16x16x32_bf16 v[86:89], v[130:133], v[224:227], v[86:89]
	v_mfma_f32_16x16x32_bf16 v[78:81], v[138:141], v[224:227], v[78:81]
	v_mfma_f32_16x16x32_bf16 v[126:129], v[134:137], v[204:207], v[126:129]
	v_mfma_f32_16x16x32_bf16 v[122:125], v[142:145], v[204:207], v[122:125]
	v_mfma_f32_16x16x32_bf16 v[118:121], v[134:137], v[212:215], v[118:121]
	v_mfma_f32_16x16x32_bf16 v[110:113], v[142:145], v[212:215], v[110:113]
	v_mfma_f32_16x16x32_bf16 v[102:105], v[134:137], v[220:223], v[102:105]
	v_mfma_f32_16x16x32_bf16 v[94:97], v[142:145], v[220:223], v[94:97]
	v_mfma_f32_16x16x32_bf16 v[86:89], v[134:137], v[234:237], v[86:89]
	v_mfma_f32_16x16x32_bf16 v[78:81], v[142:145], v[234:237], v[78:81]
	v_mfma_f32_16x16x32_bf16 v[114:117], v[146:149], v[182:185], v[114:117]
	v_mfma_f32_16x16x32_bf16 v[106:109], v[174:177], v[182:185], v[106:109]
	v_mfma_f32_16x16x32_bf16 v[98:101], v[146:149], v[208:211], v[98:101]
	v_mfma_f32_16x16x32_bf16 v[90:93], v[174:177], v[208:211], v[90:93]
	v_mfma_f32_16x16x32_bf16 v[82:85], v[146:149], v[216:219], v[82:85]
	v_mfma_f32_16x16x32_bf16 v[74:77], v[174:177], v[216:219], v[74:77]
	v_mfma_f32_16x16x32_bf16 v[70:73], v[146:149], v[224:227], v[70:73]
	v_mfma_f32_16x16x32_bf16 v[66:69], v[174:177], v[224:227], v[66:69]
	v_mfma_f32_16x16x32_bf16 v[114:117], v[150:153], v[204:207], v[114:117]
	v_mfma_f32_16x16x32_bf16 v[106:109], v[178:181], v[204:207], v[106:109]
	v_mfma_f32_16x16x32_bf16 v[98:101], v[150:153], v[212:215], v[98:101]
	v_mfma_f32_16x16x32_bf16 v[90:93], v[178:181], v[212:215], v[90:93]
	v_mfma_f32_16x16x32_bf16 v[82:85], v[150:153], v[220:223], v[82:85]
	v_mfma_f32_16x16x32_bf16 v[74:77], v[178:181], v[220:223], v[74:77]
	v_mfma_f32_16x16x32_bf16 v[70:73], v[150:153], v[234:237], v[70:73]
	v_mfma_f32_16x16x32_bf16 v[66:69], v[178:181], v[234:237], v[66:69]
	s_barrier
	s_add_i32 s44, s46, s8
	v_lshl_add_u64 v[186:187], v[186:187], 0, s[20:21]
	s_mov_b32 m0, s44
	ds_read_b128 v[182:185], v193 offset:49152
	ds_read_b128 v[204:207], v193 offset:50176
	ds_read_b128 v[208:211], v193 offset:51200
	ds_read_b128 v[212:215], v193 offset:52224
	ds_read_b128 v[216:219], v193 offset:53248
	ds_read_b128 v[220:223], v193 offset:54272
	ds_read_b128 v[224:227], v193 offset:55296
	ds_read_b128 v[234:237], v193 offset:56320
	global_load_lds_dwordx4 v[186:187], off
	s_add_i32 m0, s44, 0x2000
	s_add_u32 s42, s42, 0x100080
	v_lshl_add_u64 v[186:187], v[194:195], 0, s[20:21]
	s_addc_u32 s43, s43, 0
	s_add_i32 s44, s47, s8
	global_load_lds_dwordx4 v[186:187], off
	v_lshl_add_u64 v[186:187], s[42:43], 0, v[158:159]
	s_mov_b32 m0, s44
	s_nop 0
	global_load_lds_dwordx4 v[186:187], off
	v_lshl_add_u64 v[186:187], s[42:43], 0, v[162:163]
	s_add_i32 m0, s44, 0x2000
	s_nop 0
	global_load_lds_dwordx4 v[186:187], off
	v_lshl_add_u64 v[186:187], v[200:201], 0, s[20:21]
	s_mov_b32 m0, s50
	s_nop 0
	global_load_lds_dwordx4 v[186:187], off
	v_lshl_add_u64 v[186:187], v[238:239], 0, s[20:21]
	s_mov_b32 m0, s51
	s_nop 0
	global_load_lds_dwordx4 v[186:187], off
	s_waitcnt vmcnt(8)
	s_waitcnt lgkmcnt(0)
	s_barrier
	s_waitcnt lgkmcnt(0)
	v_mfma_f32_16x16x32_bf16 v[62:65], v[130:133], v[182:185], v[62:65]
	v_mfma_f32_16x16x32_bf16 v[58:61], v[138:141], v[182:185], v[58:61]
	v_mfma_f32_16x16x32_bf16 v[54:57], v[130:133], v[208:211], v[54:57]
	v_mfma_f32_16x16x32_bf16 v[46:49], v[138:141], v[208:211], v[46:49]
	v_mfma_f32_16x16x32_bf16 v[38:41], v[130:133], v[216:219], v[38:41]
	v_mfma_f32_16x16x32_bf16 v[30:33], v[138:141], v[216:219], v[30:33]
	v_mfma_f32_16x16x32_bf16 v[22:25], v[130:133], v[224:227], v[22:25]
	v_mfma_f32_16x16x32_bf16 v[14:17], v[138:141], v[224:227], v[14:17]
	v_mfma_f32_16x16x32_bf16 v[62:65], v[134:137], v[204:207], v[62:65]
	v_mfma_f32_16x16x32_bf16 v[58:61], v[142:145], v[204:207], v[58:61]
	v_mfma_f32_16x16x32_bf16 v[54:57], v[134:137], v[212:215], v[54:57]
	v_mfma_f32_16x16x32_bf16 v[46:49], v[142:145], v[212:215], v[46:49]
	v_mfma_f32_16x16x32_bf16 v[38:41], v[134:137], v[220:223], v[38:41]
	v_mfma_f32_16x16x32_bf16 v[30:33], v[142:145], v[220:223], v[30:33]
	v_mfma_f32_16x16x32_bf16 v[22:25], v[134:137], v[234:237], v[22:25]
	v_mfma_f32_16x16x32_bf16 v[14:17], v[142:145], v[234:237], v[14:17]
	v_mfma_f32_16x16x32_bf16 v[50:53], v[146:149], v[182:185], v[50:53]
	v_mfma_f32_16x16x32_bf16 v[42:45], v[174:177], v[182:185], v[42:45]
	v_mfma_f32_16x16x32_bf16 v[34:37], v[146:149], v[208:211], v[34:37]
	v_mfma_f32_16x16x32_bf16 v[26:29], v[174:177], v[208:211], v[26:29]
	v_mfma_f32_16x16x32_bf16 v[18:21], v[146:149], v[216:219], v[18:21]
	v_mfma_f32_16x16x32_bf16 v[10:13], v[174:177], v[216:219], v[10:13]
	v_mfma_f32_16x16x32_bf16 v[6:9], v[146:149], v[224:227], v[6:9]
	v_mfma_f32_16x16x32_bf16 v[2:5], v[174:177], v[224:227], v[2:5]
	v_mfma_f32_16x16x32_bf16 v[50:53], v[150:153], v[204:207], v[50:53]
	v_mfma_f32_16x16x32_bf16 v[42:45], v[178:181], v[204:207], v[42:45]
	v_mfma_f32_16x16x32_bf16 v[34:37], v[150:153], v[212:215], v[34:37]
	v_mfma_f32_16x16x32_bf16 v[26:29], v[178:181], v[212:215], v[26:29]
	v_mfma_f32_16x16x32_bf16 v[18:21], v[150:153], v[220:223], v[18:21]
	v_mfma_f32_16x16x32_bf16 v[10:13], v[178:181], v[220:223], v[10:13]
	v_mfma_f32_16x16x32_bf16 v[6:9], v[150:153], v[234:237], v[6:9]
	v_mfma_f32_16x16x32_bf16 v[2:5], v[178:181], v[234:237], v[2:5]
	s_add_i32 s29, s29, 2
	s_add_u32 s40, s40, 0x100
	s_addc_u32 s41, s41, 0
	s_add_u32 s15, s15, 0x100
	s_addc_u32 s27, s27, 0
	s_cmp_gt_u32 s29, 61
	s_barrier
	s_cbranch_scc0 .LBB0_412
	s_and_b64 vcc, exec, s[22:23]
	s_cbranch_vccz .LBB0_415
	s_barrier

.LBB0_514:
	ds_read_b128 v[156:159], v146
	ds_read_b128 v[160:163], v146 offset:1024
	ds_read_b128 v[164:167], v146 offset:2048
	ds_read_b128 v[168:171], v146 offset:3072
	ds_read_b128 v[172:175], v147
	s_waitcnt lgkmcnt(0)
	ds_read_b128 v[176:179], v147 offset:1024
	ds_read_b128 v[180:183], v147 offset:2048
	ds_read_b128 v[184:187], v147 offset:3072
	s_add_u32 s28, s26, 0xfff00080
	s_addc_u32 s29, s27, -1
	s_cmp_eq_u32 s50, 4
	s_cselect_b32 s31, s19, s29
	s_cselect_b32 s30, s18, s28
	s_cselect_b32 s29, s21, s49
	s_cselect_b32 s28, s20, s23
	s_mov_b32 m0, s36
	v_lshl_add_u64 v[142:143], s[26:27], 0, v[138:139]
	ds_read_b128 v[190:193], v148
	ds_read_b128 v[204:207], v148 offset:1024
	ds_read_b128 v[208:211], v148 offset:2048
	ds_read_b128 v[212:215], v148 offset:3072
	ds_read_b128 v[216:219], v148 offset:4096
	ds_read_b128 v[220:223], v148 offset:5120
	ds_read_b128 v[224:227], v148 offset:6144
	ds_read_b128 v[234:237], v148 offset:7168
	global_load_lds_dwordx4 v[142:143], off
	v_lshl_add_u64 v[142:143], s[26:27], 0, v[140:141]
	s_mov_b32 m0, s37
	s_nop 0
	global_load_lds_dwordx4 v[142:143], off
	s_waitcnt vmcnt(8)
	s_waitcnt lgkmcnt(0)
	s_barrier
	s_waitcnt lgkmcnt(0)
	v_mfma_f32_16x16x32_bf16 v[126:129], v[156:159], v[190:193], v[126:129]
	v_mfma_f32_16x16x32_bf16 v[122:125], v[164:167], v[190:193], v[122:125]
	v_mfma_f32_16x16x32_bf16 v[118:121], v[156:159], v[208:211], v[118:121]
	v_mfma_f32_16x16x32_bf16 v[110:113], v[164:167], v[208:211], v[110:113]
	v_mfma_f32_16x16x32_bf16 v[102:105], v[156:159], v[216:219], v[102:105]
	v_mfma_f32_16x16x32_bf16 v[94:97], v[164:167], v[216:219], v[94:97]
	v_mfma_f32_16x16x32_bf16 v[82:85], v[156:159], v[224:227], v[82:85]
	v_mfma_f32_16x16x32_bf16 v[74:77], v[164:167], v[224:227], v[74:77]
	v_mfma_f32_16x16x32_bf16 v[126:129], v[160:163], v[204:207], v[126:129]
	v_mfma_f32_16x16x32_bf16 v[122:125], v[168:171], v[204:207], v[122:125]
	v_mfma_f32_16x16x32_bf16 v[118:121], v[160:163], v[212:215], v[118:121]
	v_mfma_f32_16x16x32_bf16 v[110:113], v[168:171], v[212:215], v[110:113]
	v_mfma_f32_16x16x32_bf16 v[102:105], v[160:163], v[220:223], v[102:105]
	v_mfma_f32_16x16x32_bf16 v[94:97], v[168:171], v[220:223], v[94:97]
	v_mfma_f32_16x16x32_bf16 v[82:85], v[160:163], v[234:237], v[82:85]
	v_mfma_f32_16x16x32_bf16 v[74:77], v[168:171], v[234:237], v[74:77]
	v_mfma_f32_16x16x32_bf16 v[114:117], v[172:175], v[190:193], v[114:117]
	v_mfma_f32_16x16x32_bf16 v[106:109], v[180:183], v[190:193], v[106:109]
	v_mfma_f32_16x16x32_bf16 v[98:101], v[172:175], v[208:211], v[98:101]
	v_mfma_f32_16x16x32_bf16 v[90:93], v[180:183], v[208:211], v[90:93]
	v_mfma_f32_16x16x32_bf16 v[86:89], v[172:175], v[216:219], v[86:89]
	v_mfma_f32_16x16x32_bf16 v[78:81], v[180:183], v[216:219], v[78:81]
	v_mfma_f32_16x16x32_bf16 v[70:73], v[172:175], v[224:227], v[70:73]
	v_mfma_f32_16x16x32_bf16 v[66:69], v[180:183], v[224:227], v[66:69]
	v_mfma_f32_16x16x32_bf16 v[114:117], v[176:179], v[204:207], v[114:117]
	v_mfma_f32_16x16x32_bf16 v[106:109], v[184:187], v[204:207], v[106:109]
	v_mfma_f32_16x16x32_bf16 v[98:101], v[176:179], v[212:215], v[98:101]
	v_mfma_f32_16x16x32_bf16 v[90:93], v[184:187], v[212:215], v[90:93]
	v_mfma_f32_16x16x32_bf16 v[86:89], v[176:179], v[220:223], v[86:89]
	v_mfma_f32_16x16x32_bf16 v[78:81], v[184:187], v[220:223], v[78:81]
	v_mfma_f32_16x16x32_bf16 v[70:73], v[176:179], v[234:237], v[70:73]
	v_mfma_f32_16x16x32_bf16 v[66:69], v[184:187], v[234:237], v[66:69]
	s_barrier
	s_mov_b32 m0, s38
	v_lshl_add_u64 v[142:143], s[28:29], 0, v[134:135]
	s_add_u32 s52, s28, 0x20000
	ds_read_b128 v[190:193], v148 offset:16384
	ds_read_b128 v[204:207], v148 offset:17408
	ds_read_b128 v[208:211], v148 offset:18432
	ds_read_b128 v[212:215], v148 offset:19456
	ds_read_b128 v[216:219], v148 offset:20480
	ds_read_b128 v[220:223], v148 offset:21504
	ds_read_b128 v[224:227], v148 offset:22528
	ds_read_b128 v[234:237], v148 offset:23552
	global_load_lds_dwordx4 v[142:143], off
	v_lshl_add_u64 v[152:153], s[28:29], 0, v[130:131]
	s_mov_b32 m0, s39
	s_addc_u32 s53, s29, 0
	global_load_lds_dwordx4 v[152:153], off
	v_lshl_add_u64 v[194:195], s[52:53], 0, v[134:135]
	s_mov_b32 m0, s40
	v_lshl_add_u64 v[200:201], s[30:31], 0, v[132:133]
	global_load_lds_dwordx4 v[194:195], off
	v_lshl_add_u64 v[194:195], s[52:53], 0, v[130:131]
	s_mov_b32 m0, s41
	s_nop 0
	global_load_lds_dwordx4 v[194:195], off
	v_lshl_add_u64 v[194:195], s[30:31], 0, v[136:137]
	s_mov_b32 m0, s9
	s_nop 0
	global_load_lds_dwordx4 v[194:195], off
	s_mov_b32 m0, s13
	s_nop 0
	global_load_lds_dwordx4 v[200:201], off
	s_waitcnt vmcnt(8)
	s_waitcnt lgkmcnt(0)
	s_barrier
	s_waitcnt lgkmcnt(0)
	v_mfma_f32_16x16x32_bf16 v[62:65], v[156:159], v[190:193], v[62:65]
	v_mfma_f32_16x16x32_bf16 v[58:61], v[164:167], v[190:193], v[58:61]
	v_mfma_f32_16x16x32_bf16 v[54:57], v[156:159], v[208:211], v[54:57]
	v_mfma_f32_16x16x32_bf16 v[46:49], v[164:167], v[208:211], v[46:49]
	v_mfma_f32_16x16x32_bf16 v[38:41], v[156:159], v[216:219], v[38:41]
	v_mfma_f32_16x16x32_bf16 v[30:33], v[164:167], v[216:219], v[30:33]
	v_mfma_f32_16x16x32_bf16 v[22:25], v[156:159], v[224:227], v[22:25]
	v_mfma_f32_16x16x32_bf16 v[14:17], v[164:167], v[224:227], v[14:17]
	v_mfma_f32_16x16x32_bf16 v[62:65], v[160:163], v[204:207], v[62:65]
	v_mfma_f32_16x16x32_bf16 v[58:61], v[168:171], v[204:207], v[58:61]
	v_mfma_f32_16x16x32_bf16 v[54:57], v[160:163], v[212:215], v[54:57]
	v_mfma_f32_16x16x32_bf16 v[46:49], v[168:171], v[212:215], v[46:49]
	v_mfma_f32_16x16x32_bf16 v[38:41], v[160:163], v[220:223], v[38:41]
	v_mfma_f32_16x16x32_bf16 v[30:33], v[168:171], v[220:223], v[30:33]
	v_mfma_f32_16x16x32_bf16 v[22:25], v[160:163], v[234:237], v[22:25]
	v_mfma_f32_16x16x32_bf16 v[14:17], v[168:171], v[234:237], v[14:17]
	v_mfma_f32_16x16x32_bf16 v[50:53], v[172:175], v[190:193], v[50:53]
	v_mfma_f32_16x16x32_bf16 v[42:45], v[180:183], v[190:193], v[42:45]
	v_mfma_f32_16x16x32_bf16 v[34:37], v[172:175], v[208:211], v[34:37]
	v_mfma_f32_16x16x32_bf16 v[26:29], v[180:183], v[208:211], v[26:29]
	v_mfma_f32_16x16x32_bf16 v[18:21], v[172:175], v[216:219], v[18:21]
	v_mfma_f32_16x16x32_bf16 v[10:13], v[180:183], v[216:219], v[10:13]
	v_mfma_f32_16x16x32_bf16 v[6:9], v[172:175], v[224:227], v[6:9]
	v_mfma_f32_16x16x32_bf16 v[2:5], v[180:183], v[224:227], v[2:5]
	v_mfma_f32_16x16x32_bf16 v[50:53], v[176:179], v[204:207], v[50:53]
	v_mfma_f32_16x16x32_bf16 v[42:45], v[184:187], v[204:207], v[42:45]
	v_mfma_f32_16x16x32_bf16 v[34:37], v[176:179], v[212:215], v[34:37]
	v_mfma_f32_16x16x32_bf16 v[26:29], v[184:187], v[212:215], v[26:29]
	v_mfma_f32_16x16x32_bf16 v[18:21], v[176:179], v[220:223], v[18:21]
	v_mfma_f32_16x16x32_bf16 v[10:13], v[184:187], v[220:223], v[10:13]
	v_mfma_f32_16x16x32_bf16 v[6:9], v[176:179], v[234:237], v[6:9]
	v_mfma_f32_16x16x32_bf16 v[2:5], v[184:187], v[234:237], v[2:5]
	s_barrier
	ds_read_b128 v[156:159], v149
	ds_read_b128 v[160:163], v149 offset:1024
	ds_read_b128 v[164:167], v149 offset:2048
	ds_read_b128 v[168:171], v149 offset:3072
	ds_read_b128 v[172:175], v150
	ds_read_b128 v[176:179], v150 offset:1024
	ds_read_b128 v[180:183], v150 offset:2048
	ds_read_b128 v[184:187], v150 offset:3072
	s_add_u32 s30, s30, 0x100000
	s_addc_u32 s31, s31, 0
	s_mov_b32 m0, s14
	v_lshl_add_u64 v[238:239], s[30:31], 0, v[136:137]
	ds_read_b128 v[190:193], v148 offset:32768
	ds_read_b128 v[204:207], v148 offset:33792
	ds_read_b128 v[208:211], v148 offset:34816
	ds_read_b128 v[212:215], v148 offset:35840
	ds_read_b128 v[216:219], v148 offset:36864
	ds_read_b128 v[220:223], v148 offset:37888
	ds_read_b128 v[224:227], v148 offset:38912
	ds_read_b128 v[234:237], v148 offset:39936
	global_load_lds_dwordx4 v[238:239], off
	v_lshl_add_u64 v[238:239], s[30:31], 0, v[132:133]
	s_mov_b32 m0, s15
	s_nop 0
	global_load_lds_dwordx4 v[238:239], off
	s_waitcnt vmcnt(8)
	s_waitcnt lgkmcnt(0)
	s_barrier
	s_waitcnt lgkmcnt(0)
	v_mfma_f32_16x16x32_bf16 v[126:129], v[156:159], v[190:193], v[126:129]
	v_mfma_f32_16x16x32_bf16 v[122:125], v[164:167], v[190:193], v[122:125]
	v_mfma_f32_16x16x32_bf16 v[118:121], v[156:159], v[208:211], v[118:121]
	v_mfma_f32_16x16x32_bf16 v[110:113], v[164:167], v[208:211], v[110:113]
	v_mfma_f32_16x16x32_bf16 v[102:105], v[156:159], v[216:219], v[102:105]
	v_mfma_f32_16x16x32_bf16 v[94:97], v[164:167], v[216:219], v[94:97]
	v_mfma_f32_16x16x32_bf16 v[82:85], v[156:159], v[224:227], v[82:85]
	v_mfma_f32_16x16x32_bf16 v[74:77], v[164:167], v[224:227], v[74:77]
	v_mfma_f32_16x16x32_bf16 v[126:129], v[160:163], v[204:207], v[126:129]
	v_mfma_f32_16x16x32_bf16 v[122:125], v[168:171], v[204:207], v[122:125]
	v_mfma_f32_16x16x32_bf16 v[118:121], v[160:163], v[212:215], v[118:121]
	v_mfma_f32_16x16x32_bf16 v[110:113], v[168:171], v[212:215], v[110:113]
	v_mfma_f32_16x16x32_bf16 v[102:105], v[160:163], v[220:223], v[102:105]
	v_mfma_f32_16x16x32_bf16 v[94:97], v[168:171], v[220:223], v[94:97]
	v_mfma_f32_16x16x32_bf16 v[82:85], v[160:163], v[234:237], v[82:85]
	v_mfma_f32_16x16x32_bf16 v[74:77], v[168:171], v[234:237], v[74:77]
	v_mfma_f32_16x16x32_bf16 v[114:117], v[172:175], v[190:193], v[114:117]
	v_mfma_f32_16x16x32_bf16 v[106:109], v[180:183], v[190:193], v[106:109]
	v_mfma_f32_16x16x32_bf16 v[98:101], v[172:175], v[208:211], v[98:101]
	v_mfma_f32_16x16x32_bf16 v[90:93], v[180:183], v[208:211], v[90:93]
	v_mfma_f32_16x16x32_bf16 v[86:89], v[172:175], v[216:219], v[86:89]
	v_mfma_f32_16x16x32_bf16 v[78:81], v[180:183], v[216:219], v[78:81]
	v_mfma_f32_16x16x32_bf16 v[70:73], v[172:175], v[224:227], v[70:73]
	v_mfma_f32_16x16x32_bf16 v[66:69], v[180:183], v[224:227], v[66:69]
	v_mfma_f32_16x16x32_bf16 v[114:117], v[176:179], v[204:207], v[114:117]
	v_mfma_f32_16x16x32_bf16 v[106:109], v[184:187], v[204:207], v[106:109]
	v_mfma_f32_16x16x32_bf16 v[98:101], v[176:179], v[212:215], v[98:101]
	v_mfma_f32_16x16x32_bf16 v[90:93], v[184:187], v[212:215], v[90:93]
	v_mfma_f32_16x16x32_bf16 v[86:89], v[176:179], v[220:223], v[86:89]
	v_mfma_f32_16x16x32_bf16 v[78:81], v[184:187], v[220:223], v[78:81]
	v_mfma_f32_16x16x32_bf16 v[70:73], v[176:179], v[234:237], v[70:73]
	v_mfma_f32_16x16x32_bf16 v[66:69], v[184:187], v[234:237], v[66:69]
	s_barrier
	s_mov_b32 m0, s42
	v_lshl_add_u64 v[142:143], v[142:143], 0, s[4:5]
	s_add_u32 s28, s28, 0x20080
	ds_read_b128 v[190:193], v148 offset:49152
	ds_read_b128 v[204:207], v148 offset:50176
	ds_read_b128 v[208:211], v148 offset:51200
	ds_read_b128 v[212:215], v148 offset:52224
	ds_read_b128 v[216:219], v148 offset:53248
	ds_read_b128 v[220:223], v148 offset:54272
	ds_read_b128 v[224:227], v148 offset:55296
	ds_read_b128 v[234:237], v148 offset:56320
	global_load_lds_dwordx4 v[142:143], off
	v_lshl_add_u64 v[142:143], v[152:153], 0, s[4:5]
	s_mov_b32 m0, s43
	s_addc_u32 s29, s29, 0
	global_load_lds_dwordx4 v[142:143], off
	v_lshl_add_u64 v[142:143], s[28:29], 0, v[134:135]
	s_mov_b32 m0, s44
	s_nop 0
	global_load_lds_dwordx4 v[142:143], off
	v_lshl_add_u64 v[142:143], s[28:29], 0, v[130:131]
	s_mov_b32 m0, s45
	s_nop 0
	global_load_lds_dwordx4 v[142:143], off
	v_lshl_add_u64 v[142:143], v[194:195], 0, s[4:5]
	s_mov_b32 m0, s34
	s_nop 0
	global_load_lds_dwordx4 v[142:143], off
	v_lshl_add_u64 v[142:143], v[200:201], 0, s[4:5]
	s_mov_b32 m0, s35
	s_nop 0
	global_load_lds_dwordx4 v[142:143], off
	s_waitcnt vmcnt(8)
	s_waitcnt lgkmcnt(0)
	s_barrier
	s_waitcnt lgkmcnt(0)
	v_mfma_f32_16x16x32_bf16 v[62:65], v[156:159], v[190:193], v[62:65]
	v_mfma_f32_16x16x32_bf16 v[58:61], v[164:167], v[190:193], v[58:61]
	v_mfma_f32_16x16x32_bf16 v[54:57], v[156:159], v[208:211], v[54:57]
	v_mfma_f32_16x16x32_bf16 v[46:49], v[164:167], v[208:211], v[46:49]
	v_mfma_f32_16x16x32_bf16 v[38:41], v[156:159], v[216:219], v[38:41]
	v_mfma_f32_16x16x32_bf16 v[30:33], v[164:167], v[216:219], v[30:33]
	v_mfma_f32_16x16x32_bf16 v[22:25], v[156:159], v[224:227], v[22:25]
	v_mfma_f32_16x16x32_bf16 v[14:17], v[164:167], v[224:227], v[14:17]
	v_mfma_f32_16x16x32_bf16 v[62:65], v[160:163], v[204:207], v[62:65]
	v_mfma_f32_16x16x32_bf16 v[58:61], v[168:171], v[204:207], v[58:61]
	v_mfma_f32_16x16x32_bf16 v[54:57], v[160:163], v[212:215], v[54:57]
	v_mfma_f32_16x16x32_bf16 v[46:49], v[168:171], v[212:215], v[46:49]
	v_mfma_f32_16x16x32_bf16 v[38:41], v[160:163], v[220:223], v[38:41]
	v_mfma_f32_16x16x32_bf16 v[30:33], v[168:171], v[220:223], v[30:33]
	v_mfma_f32_16x16x32_bf16 v[22:25], v[160:163], v[234:237], v[22:25]
	v_mfma_f32_16x16x32_bf16 v[14:17], v[168:171], v[234:237], v[14:17]
	v_mfma_f32_16x16x32_bf16 v[50:53], v[172:175], v[190:193], v[50:53]
	v_mfma_f32_16x16x32_bf16 v[42:45], v[180:183], v[190:193], v[42:45]
	v_mfma_f32_16x16x32_bf16 v[34:37], v[172:175], v[208:211], v[34:37]
	v_mfma_f32_16x16x32_bf16 v[26:29], v[180:183], v[208:211], v[26:29]
	v_mfma_f32_16x16x32_bf16 v[18:21], v[172:175], v[216:219], v[18:21]
	v_mfma_f32_16x16x32_bf16 v[10:13], v[180:183], v[216:219], v[10:13]
	v_mfma_f32_16x16x32_bf16 v[6:9], v[172:175], v[224:227], v[6:9]
	v_mfma_f32_16x16x32_bf16 v[2:5], v[180:183], v[224:227], v[2:5]
	v_mfma_f32_16x16x32_bf16 v[50:53], v[176:179], v[204:207], v[50:53]
	v_mfma_f32_16x16x32_bf16 v[42:45], v[184:187], v[204:207], v[42:45]
	v_mfma_f32_16x16x32_bf16 v[34:37], v[176:179], v[212:215], v[34:37]
	v_mfma_f32_16x16x32_bf16 v[26:29], v[184:187], v[212:215], v[26:29]
	v_mfma_f32_16x16x32_bf16 v[18:21], v[176:179], v[220:223], v[18:21]
	v_mfma_f32_16x16x32_bf16 v[10:13], v[184:187], v[220:223], v[10:13]
	v_mfma_f32_16x16x32_bf16 v[6:9], v[176:179], v[234:237], v[6:9]
	v_mfma_f32_16x16x32_bf16 v[2:5], v[184:187], v[234:237], v[2:5]
	s_add_i32 s50, s50, 2
	s_add_u32 s26, s26, 0x100
	s_addc_u32 s27, s27, 0
	s_add_u32 s23, s23, 0x100
	s_addc_u32 s49, s49, 0
	s_cmp_gt_u32 s50, 5
	s_barrier
	s_cbranch_scc0 .LBB0_514
	s_and_b64 vcc, exec, s[6:7]
	s_cbranch_vccz .LBB0_517
	s_barrier

.LBB0_734:
	ds_read_b128 v[158:161], v227
	ds_read_b128 v[154:157], v227 offset:1024
	ds_read_b128 v[150:153], v227 offset:2048
	ds_read_b128 v[146:149], v227 offset:3072
	ds_read_b128 v[62:65], v233
	ds_read_b128 v[58:61], v233 offset:1024
	ds_read_b128 v[54:57], v233 offset:2048
	ds_read_b128 v[50:53], v233 offset:3072
	s_add_u32 s14, s30, s34
	s_addc_u32 s15, s31, s35
	s_add_u32 s14, s14, 0x100
	s_addc_u32 s15, s15, 0
	s_add_u32 s25, s77, s34
	s_addc_u32 s29, s78, s35
	s_cmpk_eq_i32 s34, 0xf00
	s_cselect_b32 s41, s31, s15
	s_cselect_b32 s40, s30, s14
	s_cselect_b32 s39, s1, s29
	s_cselect_b32 s38, s0, s25
	s_add_i32 s66, s23, 0xc000
	v_lshl_add_u64 v[240:241], v[162:163], 0, s[34:35]
	s_mov_b32 m0, s66
	s_add_i32 s67, s23, 0xe000
	ds_read_b128 v[166:169], v226
	ds_read_b128 v[170:173], v226 offset:1024
	ds_read_b128 v[174:177], v226 offset:2048
	ds_read_b128 v[178:181], v226 offset:3072
	ds_read_b128 v[182:185], v226 offset:4096
	ds_read_b128 v[186:189], v226 offset:5120
	ds_read_b128 v[190:193], v226 offset:6144
	ds_read_b128 v[236:239], v226 offset:7168
	global_load_lds_dwordx4 v[240:241], off
	v_lshl_add_u64 v[240:241], v[164:165], 0, s[34:35]
	s_mov_b32 m0, s67
	s_nop 0
	global_load_lds_dwordx4 v[240:241], off
	s_waitcnt vmcnt(8)
	s_waitcnt lgkmcnt(0)
	s_barrier
	s_waitcnt lgkmcnt(0)
	v_mfma_i32_16x16x64_i8 v[142:145], v[158:161], v[166:169], v[142:145]
	v_mfma_i32_16x16x64_i8 v[142:145], v[154:157], v[170:173], v[142:145]
	v_mfma_i32_16x16x64_i8 v[138:141], v[150:153], v[166:169], v[138:141]
	v_mfma_i32_16x16x64_i8 v[138:141], v[146:149], v[170:173], v[138:141]
	v_mfma_i32_16x16x64_i8 v[126:129], v[158:161], v[174:177], v[126:129]
	v_mfma_i32_16x16x64_i8 v[126:129], v[154:157], v[178:181], v[126:129]
	v_mfma_i32_16x16x64_i8 v[122:125], v[150:153], v[174:177], v[122:125]
	v_mfma_i32_16x16x64_i8 v[122:125], v[146:149], v[178:181], v[122:125]
	v_mfma_i32_16x16x64_i8 v[110:113], v[158:161], v[182:185], v[110:113]
	v_mfma_i32_16x16x64_i8 v[110:113], v[154:157], v[186:189], v[110:113]
	v_mfma_i32_16x16x64_i8 v[106:109], v[150:153], v[182:185], v[106:109]
	v_mfma_i32_16x16x64_i8 v[106:109], v[146:149], v[186:189], v[106:109]
	v_mfma_i32_16x16x64_i8 v[94:97], v[158:161], v[190:193], v[94:97]
	v_mfma_i32_16x16x64_i8 v[94:97], v[154:157], v[236:239], v[94:97]
	v_mfma_i32_16x16x64_i8 v[90:93], v[150:153], v[190:193], v[90:93]
	v_mfma_i32_16x16x64_i8 v[90:93], v[146:149], v[236:239], v[90:93]
	v_mfma_i32_16x16x64_i8 v[134:137], v[62:65], v[166:169], v[134:137]
	v_mfma_i32_16x16x64_i8 v[134:137], v[58:61], v[170:173], v[134:137]
	v_mfma_i32_16x16x64_i8 v[130:133], v[54:57], v[166:169], v[130:133]
	v_mfma_i32_16x16x64_i8 v[130:133], v[50:53], v[170:173], v[130:133]
	v_mfma_i32_16x16x64_i8 v[118:121], v[62:65], v[174:177], v[118:121]
	v_mfma_i32_16x16x64_i8 v[118:121], v[58:61], v[178:181], v[118:121]
	v_mfma_i32_16x16x64_i8 v[114:117], v[54:57], v[174:177], v[114:117]
	v_mfma_i32_16x16x64_i8 v[114:117], v[50:53], v[178:181], v[114:117]
	v_mfma_i32_16x16x64_i8 v[102:105], v[62:65], v[182:185], v[102:105]
	v_mfma_i32_16x16x64_i8 v[102:105], v[58:61], v[186:189], v[102:105]
	v_mfma_i32_16x16x64_i8 v[98:101], v[54:57], v[182:185], v[98:101]
	v_mfma_i32_16x16x64_i8 v[98:101], v[50:53], v[186:189], v[98:101]
	v_mfma_i32_16x16x64_i8 v[86:89], v[62:65], v[190:193], v[86:89]
	v_mfma_i32_16x16x64_i8 v[86:89], v[58:61], v[236:239], v[86:89]
	v_mfma_i32_16x16x64_i8 v[82:85], v[54:57], v[190:193], v[82:85]
	v_mfma_i32_16x16x64_i8 v[82:85], v[50:53], v[236:239], v[82:85]
	s_barrier
	s_add_i32 s68, s60, s21
	s_add_i32 s69, s68, 0x2000
	v_lshl_add_u64 v[166:167], s[38:39], 0, v[202:203]
	s_mov_b32 m0, s68
	s_add_u32 s14, s38, 0x80000
	ds_read_b128 v[174:177], v226 offset:16384
	ds_read_b128 v[178:181], v226 offset:17408
	ds_read_b128 v[182:185], v226 offset:18432
	ds_read_b128 v[186:189], v226 offset:19456
	ds_read_b128 v[190:193], v226 offset:20480
	ds_read_b128 v[236:239], v226 offset:21504
	ds_read_b128 v[240:243], v226 offset:22528
	ds_read_b128 v[244:247], v226 offset:23552
	global_load_lds_dwordx4 v[166:167], off
	v_lshl_add_u64 v[168:169], s[38:39], 0, v[206:207]
	s_mov_b32 m0, s69
	s_addc_u32 s15, s39, 0
	s_add_i32 s70, s61, s21
	global_load_lds_dwordx4 v[168:169], off
	v_lshl_add_u64 v[170:171], s[14:15], 0, v[202:203]
	s_mov_b32 m0, s70
	s_add_i32 s71, s70, 0x2000
	global_load_lds_dwordx4 v[170:171], off
	v_lshl_add_u64 v[170:171], s[14:15], 0, v[206:207]
	s_mov_b32 m0, s71
	v_lshl_add_u64 v[172:173], s[40:41], 0, v[204:205]
	global_load_lds_dwordx4 v[170:171], off
	v_lshl_add_u64 v[170:171], s[40:41], 0, v[194:195]
	s_mov_b32 m0, s23
	s_nop 0
	global_load_lds_dwordx4 v[170:171], off
	s_mov_b32 m0, s42
	s_nop 0
	global_load_lds_dwordx4 v[172:173], off
	s_waitcnt vmcnt(8)
	s_waitcnt lgkmcnt(0)
	s_barrier
	s_waitcnt lgkmcnt(0)
	v_mfma_i32_16x16x64_i8 v[78:81], v[158:161], v[174:177], v[78:81]
	v_mfma_i32_16x16x64_i8 v[78:81], v[154:157], v[178:181], v[78:81]
	v_mfma_i32_16x16x64_i8 v[74:77], v[150:153], v[174:177], v[74:77]
	v_mfma_i32_16x16x64_i8 v[74:77], v[146:149], v[178:181], v[74:77]
	v_mfma_i32_16x16x64_i8 v[46:49], v[158:161], v[182:185], v[46:49]
	v_mfma_i32_16x16x64_i8 v[46:49], v[154:157], v[186:189], v[46:49]
	v_mfma_i32_16x16x64_i8 v[42:45], v[150:153], v[182:185], v[42:45]
	v_mfma_i32_16x16x64_i8 v[42:45], v[146:149], v[186:189], v[42:45]
	v_mfma_i32_16x16x64_i8 v[30:33], v[158:161], v[190:193], v[30:33]
	v_mfma_i32_16x16x64_i8 v[30:33], v[154:157], v[236:239], v[30:33]
	v_mfma_i32_16x16x64_i8 v[26:29], v[150:153], v[190:193], v[26:29]
	v_mfma_i32_16x16x64_i8 v[26:29], v[146:149], v[236:239], v[26:29]
	v_mfma_i32_16x16x64_i8 v[14:17], v[158:161], v[240:243], v[14:17]
	v_mfma_i32_16x16x64_i8 v[14:17], v[154:157], v[244:247], v[14:17]
	v_mfma_i32_16x16x64_i8 v[10:13], v[150:153], v[240:243], v[10:13]
	v_mfma_i32_16x16x64_i8 v[10:13], v[146:149], v[244:247], v[10:13]
	v_mfma_i32_16x16x64_i8 v[70:73], v[62:65], v[174:177], v[70:73]
	v_mfma_i32_16x16x64_i8 v[70:73], v[58:61], v[178:181], v[70:73]
	v_mfma_i32_16x16x64_i8 v[66:69], v[54:57], v[174:177], v[66:69]
	v_mfma_i32_16x16x64_i8 v[66:69], v[50:53], v[178:181], v[66:69]
	v_mfma_i32_16x16x64_i8 v[38:41], v[62:65], v[182:185], v[38:41]
	v_mfma_i32_16x16x64_i8 v[38:41], v[58:61], v[186:189], v[38:41]
	v_mfma_i32_16x16x64_i8 v[34:37], v[54:57], v[182:185], v[34:37]
	v_mfma_i32_16x16x64_i8 v[34:37], v[50:53], v[186:189], v[34:37]
	v_mfma_i32_16x16x64_i8 v[22:25], v[62:65], v[190:193], v[22:25]
	v_mfma_i32_16x16x64_i8 v[22:25], v[58:61], v[236:239], v[22:25]
	v_mfma_i32_16x16x64_i8 v[18:21], v[54:57], v[190:193], v[18:21]
	v_mfma_i32_16x16x64_i8 v[18:21], v[50:53], v[236:239], v[18:21]
	v_mfma_i32_16x16x64_i8 v[6:9], v[62:65], v[240:243], v[6:9]
	v_mfma_i32_16x16x64_i8 v[6:9], v[58:61], v[244:247], v[6:9]
	v_mfma_i32_16x16x64_i8 v[2:5], v[54:57], v[240:243], v[2:5]
	v_mfma_i32_16x16x64_i8 v[2:5], v[50:53], v[244:247], v[2:5]
	s_barrier
	s_add_i32 s72, 0, 0x18000
	v_add_u32_e32 v235, s72, v225
	s_add_i32 s74, 0, 0x1c000
	v_add_u32_e32 v236, s74, v225
	ds_read_b128 v[50:53], v235
	ds_read_b128 v[54:57], v235 offset:1024
	ds_read_b128 v[58:61], v235 offset:2048
	ds_read_b128 v[62:65], v235 offset:3072
	ds_read_b128 v[146:149], v236
	ds_read_b128 v[150:153], v236 offset:1024
	ds_read_b128 v[154:157], v236 offset:2048
	ds_read_b128 v[158:161], v236 offset:3072
	s_add_u32 s14, s40, 0x80000
	s_addc_u32 s15, s41, 0
	s_mov_b32 m0, s43
	v_lshl_add_u64 v[250:251], s[14:15], 0, v[194:195]
	ds_read_b128 v[174:177], v226 offset:32768
	ds_read_b128 v[178:181], v226 offset:33792
	ds_read_b128 v[182:185], v226 offset:34816
	ds_read_b128 v[186:189], v226 offset:35840
	ds_read_b128 v[190:193], v226 offset:36864
	ds_read_b128 v[238:241], v226 offset:37888
	ds_read_b128 v[242:245], v226 offset:38912
	ds_read_b128 v[246:249], v226 offset:39936
	global_load_lds_dwordx4 v[250:251], off
	v_lshl_add_u64 v[250:251], s[14:15], 0, v[204:205]
	s_mov_b32 m0, s44
	s_nop 0
	global_load_lds_dwordx4 v[250:251], off
	s_waitcnt vmcnt(8)
	s_waitcnt lgkmcnt(0)
	s_barrier
	s_waitcnt lgkmcnt(0)
	v_mfma_i32_16x16x64_i8 v[142:145], v[50:53], v[174:177], v[142:145]
	v_mfma_i32_16x16x64_i8 v[142:145], v[54:57], v[178:181], v[142:145]
	v_mfma_i32_16x16x64_i8 v[138:141], v[58:61], v[174:177], v[138:141]
	v_mfma_i32_16x16x64_i8 v[138:141], v[62:65], v[178:181], v[138:141]
	v_mfma_i32_16x16x64_i8 v[126:129], v[50:53], v[182:185], v[126:129]
	v_mfma_i32_16x16x64_i8 v[126:129], v[54:57], v[186:189], v[126:129]
	v_mfma_i32_16x16x64_i8 v[122:125], v[58:61], v[182:185], v[122:125]
	v_mfma_i32_16x16x64_i8 v[122:125], v[62:65], v[186:189], v[122:125]
	v_mfma_i32_16x16x64_i8 v[110:113], v[50:53], v[190:193], v[110:113]
	v_mfma_i32_16x16x64_i8 v[110:113], v[54:57], v[238:241], v[110:113]
	v_mfma_i32_16x16x64_i8 v[106:109], v[58:61], v[190:193], v[106:109]
	v_mfma_i32_16x16x64_i8 v[106:109], v[62:65], v[238:241], v[106:109]
	v_mfma_i32_16x16x64_i8 v[94:97], v[50:53], v[242:245], v[94:97]
	v_mfma_i32_16x16x64_i8 v[94:97], v[54:57], v[246:249], v[94:97]
	v_mfma_i32_16x16x64_i8 v[90:93], v[58:61], v[242:245], v[90:93]
	v_mfma_i32_16x16x64_i8 v[90:93], v[62:65], v[246:249], v[90:93]
	v_mfma_i32_16x16x64_i8 v[134:137], v[146:149], v[174:177], v[134:137]
	v_mfma_i32_16x16x64_i8 v[134:137], v[150:153], v[178:181], v[134:137]
	v_mfma_i32_16x16x64_i8 v[130:133], v[154:157], v[174:177], v[130:133]
	v_mfma_i32_16x16x64_i8 v[130:133], v[158:161], v[178:181], v[130:133]
	v_mfma_i32_16x16x64_i8 v[118:121], v[146:149], v[182:185], v[118:121]
	v_mfma_i32_16x16x64_i8 v[118:121], v[150:153], v[186:189], v[118:121]
	v_mfma_i32_16x16x64_i8 v[114:117], v[154:157], v[182:185], v[114:117]
	v_mfma_i32_16x16x64_i8 v[114:117], v[158:161], v[186:189], v[114:117]
	v_mfma_i32_16x16x64_i8 v[102:105], v[146:149], v[190:193], v[102:105]
	v_mfma_i32_16x16x64_i8 v[102:105], v[150:153], v[238:241], v[102:105]
	v_mfma_i32_16x16x64_i8 v[98:101], v[154:157], v[190:193], v[98:101]
	v_mfma_i32_16x16x64_i8 v[98:101], v[158:161], v[238:241], v[98:101]
	v_mfma_i32_16x16x64_i8 v[86:89], v[146:149], v[242:245], v[86:89]
	v_mfma_i32_16x16x64_i8 v[86:89], v[150:153], v[246:249], v[86:89]
	v_mfma_i32_16x16x64_i8 v[82:85], v[154:157], v[242:245], v[82:85]
	v_mfma_i32_16x16x64_i8 v[82:85], v[158:161], v[246:249], v[82:85]
	s_barrier
	s_add_i32 s72, s72, s21
	s_add_i32 s73, s72, 0x2000
	v_lshl_add_u64 v[166:167], v[166:167], 0, s[6:7]
	s_mov_b32 m0, s72
	s_add_u32 s14, s38, 0x80080
	ds_read_b128 v[174:177], v226 offset:49152
	ds_read_b128 v[178:181], v226 offset:50176
	ds_read_b128 v[182:185], v226 offset:51200
	ds_read_b128 v[186:189], v226 offset:52224
	ds_read_b128 v[190:193], v226 offset:53248
	ds_read_b128 v[238:241], v226 offset:54272
	ds_read_b128 v[242:245], v226 offset:55296
	ds_read_b128 v[246:249], v226 offset:56320
	global_load_lds_dwordx4 v[166:167], off
	v_lshl_add_u64 v[166:167], v[168:169], 0, s[6:7]
	s_mov_b32 m0, s73
	s_addc_u32 s15, s39, 0
	s_add_i32 s74, s74, s21
	global_load_lds_dwordx4 v[166:167], off
	v_lshl_add_u64 v[166:167], s[14:15], 0, v[202:203]
	s_mov_b32 m0, s74
	s_add_i32 s75, s74, 0x2000
	global_load_lds_dwordx4 v[166:167], off
	v_lshl_add_u64 v[166:167], s[14:15], 0, v[206:207]
	s_mov_b32 m0, s75
	s_nop 0
	global_load_lds_dwordx4 v[166:167], off
	v_lshl_add_u64 v[166:167], v[170:171], 0, s[6:7]
	s_mov_b32 m0, s51
	s_nop 0
	global_load_lds_dwordx4 v[166:167], off
	v_lshl_add_u64 v[166:167], v[172:173], 0, s[6:7]
	s_mov_b32 m0, s53
	s_nop 0
	global_load_lds_dwordx4 v[166:167], off
	s_waitcnt vmcnt(8)
	s_waitcnt lgkmcnt(0)
	s_barrier
	s_waitcnt lgkmcnt(0)
	v_mfma_i32_16x16x64_i8 v[78:81], v[50:53], v[174:177], v[78:81]
	v_mfma_i32_16x16x64_i8 v[78:81], v[54:57], v[178:181], v[78:81]
	v_mfma_i32_16x16x64_i8 v[74:77], v[58:61], v[174:177], v[74:77]
	v_mfma_i32_16x16x64_i8 v[74:77], v[62:65], v[178:181], v[74:77]
	v_mfma_i32_16x16x64_i8 v[46:49], v[50:53], v[182:185], v[46:49]
	v_mfma_i32_16x16x64_i8 v[46:49], v[54:57], v[186:189], v[46:49]
	v_mfma_i32_16x16x64_i8 v[42:45], v[58:61], v[182:185], v[42:45]
	v_mfma_i32_16x16x64_i8 v[42:45], v[62:65], v[186:189], v[42:45]
	v_mfma_i32_16x16x64_i8 v[30:33], v[50:53], v[190:193], v[30:33]
	v_mfma_i32_16x16x64_i8 v[30:33], v[54:57], v[238:241], v[30:33]
	v_mfma_i32_16x16x64_i8 v[26:29], v[58:61], v[190:193], v[26:29]
	v_mfma_i32_16x16x64_i8 v[26:29], v[62:65], v[238:241], v[26:29]
	v_mfma_i32_16x16x64_i8 v[14:17], v[50:53], v[242:245], v[14:17]
	v_mfma_i32_16x16x64_i8 v[14:17], v[54:57], v[246:249], v[14:17]
	v_mfma_i32_16x16x64_i8 v[10:13], v[58:61], v[242:245], v[10:13]
	v_mfma_i32_16x16x64_i8 v[10:13], v[62:65], v[246:249], v[10:13]
	v_mfma_i32_16x16x64_i8 v[70:73], v[146:149], v[174:177], v[70:73]
	v_mfma_i32_16x16x64_i8 v[70:73], v[150:153], v[178:181], v[70:73]
	v_mfma_i32_16x16x64_i8 v[66:69], v[154:157], v[174:177], v[66:69]
	v_mfma_i32_16x16x64_i8 v[66:69], v[158:161], v[178:181], v[66:69]
	v_mfma_i32_16x16x64_i8 v[38:41], v[146:149], v[182:185], v[38:41]
	v_mfma_i32_16x16x64_i8 v[38:41], v[150:153], v[186:189], v[38:41]
	v_mfma_i32_16x16x64_i8 v[34:37], v[154:157], v[182:185], v[34:37]
	v_mfma_i32_16x16x64_i8 v[34:37], v[158:161], v[186:189], v[34:37]
	v_mfma_i32_16x16x64_i8 v[22:25], v[146:149], v[190:193], v[22:25]
	v_mfma_i32_16x16x64_i8 v[22:25], v[150:153], v[238:241], v[22:25]
	v_mfma_i32_16x16x64_i8 v[18:21], v[154:157], v[190:193], v[18:21]
	v_mfma_i32_16x16x64_i8 v[18:21], v[158:161], v[238:241], v[18:21]
	v_mfma_i32_16x16x64_i8 v[6:9], v[146:149], v[242:245], v[6:9]
	v_mfma_i32_16x16x64_i8 v[6:9], v[150:153], v[246:249], v[6:9]
	v_mfma_i32_16x16x64_i8 v[2:5], v[154:157], v[242:245], v[2:5]
	v_mfma_i32_16x16x64_i8 v[2:5], v[158:161], v[246:249], v[2:5]
	s_add_i32 s3, s3, 2
	s_add_u32 s34, s34, 0x100
	s_addc_u32 s35, s35, 0
	s_cmp_gt_u32 s3, 29
	s_barrier
	s_cbranch_scc0 .LBB0_734
	s_nop 15
	s_nop 15
	s_and_b64 vcc, exec, s[8:9]
	s_cbranch_vccz .LBB0_737
	s_barrier

.LBB0_740:
	ds_read_b128 v[158:161], v227
	ds_read_b128 v[154:157], v227 offset:1024
	ds_read_b128 v[150:153], v227 offset:2048
	ds_read_b128 v[146:149], v227 offset:3072
	ds_read_b128 v[62:65], v233
	ds_read_b128 v[58:61], v233 offset:1024
	ds_read_b128 v[54:57], v233 offset:2048
	ds_read_b128 v[50:53], v233 offset:3072
	s_add_u32 s36, s38, 0xfff80080
	s_addc_u32 s37, s39, -1
	s_cmp_eq_u32 s33, 28
	s_cselect_b32 s41, s1, s37
	s_cselect_b32 s40, s0, s36
	s_cselect_b32 s37, s15, s29
	s_cselect_b32 s36, s14, s25
	s_mov_b32 m0, s66
	v_lshl_add_u64 v[238:239], s[38:39], 0, v[208:209]
	ds_read_b128 v[162:165], v226
	ds_read_b128 v[166:169], v226 offset:1024
	ds_read_b128 v[170:173], v226 offset:2048
	ds_read_b128 v[174:177], v226 offset:3072
	ds_read_b128 v[178:181], v226 offset:4096
	ds_read_b128 v[182:185], v226 offset:5120
	ds_read_b128 v[186:189], v226 offset:6144
	ds_read_b128 v[190:193], v226 offset:7168
	global_load_lds_dwordx4 v[238:239], off
	v_lshl_add_u64 v[238:239], s[38:39], 0, v[212:213]
	s_mov_b32 m0, s67
	s_nop 0
	global_load_lds_dwordx4 v[238:239], off
	s_waitcnt vmcnt(8)
	s_waitcnt lgkmcnt(0)
	s_barrier
	s_waitcnt lgkmcnt(0)
	v_mfma_i32_16x16x64_i8 v[142:145], v[158:161], v[162:165], v[142:145]
	v_mfma_i32_16x16x64_i8 v[142:145], v[154:157], v[166:169], v[142:145]
	v_mfma_i32_16x16x64_i8 v[138:141], v[150:153], v[162:165], v[138:141]
	v_mfma_i32_16x16x64_i8 v[138:141], v[146:149], v[166:169], v[138:141]
	v_mfma_i32_16x16x64_i8 v[126:129], v[158:161], v[170:173], v[126:129]
	v_mfma_i32_16x16x64_i8 v[126:129], v[154:157], v[174:177], v[126:129]
	v_mfma_i32_16x16x64_i8 v[122:125], v[150:153], v[170:173], v[122:125]
	v_mfma_i32_16x16x64_i8 v[122:125], v[146:149], v[174:177], v[122:125]
	v_mfma_i32_16x16x64_i8 v[110:113], v[158:161], v[178:181], v[110:113]
	v_mfma_i32_16x16x64_i8 v[110:113], v[154:157], v[182:185], v[110:113]
	v_mfma_i32_16x16x64_i8 v[106:109], v[150:153], v[178:181], v[106:109]
	v_mfma_i32_16x16x64_i8 v[106:109], v[146:149], v[182:185], v[106:109]
	v_mfma_i32_16x16x64_i8 v[94:97], v[158:161], v[186:189], v[94:97]
	v_mfma_i32_16x16x64_i8 v[94:97], v[154:157], v[190:193], v[94:97]
	v_mfma_i32_16x16x64_i8 v[90:93], v[150:153], v[186:189], v[90:93]
	v_mfma_i32_16x16x64_i8 v[90:93], v[146:149], v[190:193], v[90:93]
	v_mfma_i32_16x16x64_i8 v[134:137], v[62:65], v[162:165], v[134:137]
	v_mfma_i32_16x16x64_i8 v[134:137], v[58:61], v[166:169], v[134:137]
	v_mfma_i32_16x16x64_i8 v[130:133], v[54:57], v[162:165], v[130:133]
	v_mfma_i32_16x16x64_i8 v[130:133], v[50:53], v[166:169], v[130:133]
	v_mfma_i32_16x16x64_i8 v[118:121], v[62:65], v[170:173], v[118:121]
	v_mfma_i32_16x16x64_i8 v[118:121], v[58:61], v[174:177], v[118:121]
	v_mfma_i32_16x16x64_i8 v[114:117], v[54:57], v[170:173], v[114:117]
	v_mfma_i32_16x16x64_i8 v[114:117], v[50:53], v[174:177], v[114:117]
	v_mfma_i32_16x16x64_i8 v[102:105], v[62:65], v[178:181], v[102:105]
	v_mfma_i32_16x16x64_i8 v[102:105], v[58:61], v[182:185], v[102:105]
	v_mfma_i32_16x16x64_i8 v[98:101], v[54:57], v[178:181], v[98:101]
	v_mfma_i32_16x16x64_i8 v[98:101], v[50:53], v[182:185], v[98:101]
	v_mfma_i32_16x16x64_i8 v[86:89], v[62:65], v[186:189], v[86:89]
	v_mfma_i32_16x16x64_i8 v[86:89], v[58:61], v[190:193], v[86:89]
	v_mfma_i32_16x16x64_i8 v[82:85], v[54:57], v[186:189], v[82:85]
	v_mfma_i32_16x16x64_i8 v[82:85], v[50:53], v[190:193], v[82:85]
	s_barrier
	s_mov_b32 m0, s68
	v_lshl_add_u64 v[162:163], s[36:37], 0, v[202:203]
	s_add_u32 s80, s36, 0x80000
	ds_read_b128 v[170:173], v226 offset:16384
	ds_read_b128 v[174:177], v226 offset:17408
	ds_read_b128 v[178:181], v226 offset:18432
	ds_read_b128 v[182:185], v226 offset:19456
	ds_read_b128 v[186:189], v226 offset:20480
	ds_read_b128 v[190:193], v226 offset:21504
	ds_read_b128 v[238:241], v226 offset:22528
	ds_read_b128 v[242:245], v226 offset:23552
	global_load_lds_dwordx4 v[162:163], off
	v_lshl_add_u64 v[164:165], s[36:37], 0, v[206:207]
	s_mov_b32 m0, s69
	s_addc_u32 s81, s37, 0
	global_load_lds_dwordx4 v[164:165], off
	v_lshl_add_u64 v[166:167], s[80:81], 0, v[202:203]
	s_mov_b32 m0, s70
	v_lshl_add_u64 v[168:169], s[40:41], 0, v[204:205]
	global_load_lds_dwordx4 v[166:167], off
	v_lshl_add_u64 v[166:167], s[80:81], 0, v[206:207]
	s_mov_b32 m0, s71
	s_nop 0
	global_load_lds_dwordx4 v[166:167], off
	v_lshl_add_u64 v[166:167], s[40:41], 0, v[194:195]
	s_mov_b32 m0, s23
	s_nop 0
	global_load_lds_dwordx4 v[166:167], off
	s_mov_b32 m0, s42
	s_nop 0
	global_load_lds_dwordx4 v[168:169], off
	s_waitcnt vmcnt(8)
	s_waitcnt lgkmcnt(0)
	s_barrier
	s_waitcnt lgkmcnt(0)
	v_mfma_i32_16x16x64_i8 v[78:81], v[158:161], v[170:173], v[78:81]
	v_mfma_i32_16x16x64_i8 v[78:81], v[154:157], v[174:177], v[78:81]
	v_mfma_i32_16x16x64_i8 v[74:77], v[150:153], v[170:173], v[74:77]
	v_mfma_i32_16x16x64_i8 v[74:77], v[146:149], v[174:177], v[74:77]
	v_mfma_i32_16x16x64_i8 v[46:49], v[158:161], v[178:181], v[46:49]
	v_mfma_i32_16x16x64_i8 v[46:49], v[154:157], v[182:185], v[46:49]
	v_mfma_i32_16x16x64_i8 v[42:45], v[150:153], v[178:181], v[42:45]
	v_mfma_i32_16x16x64_i8 v[42:45], v[146:149], v[182:185], v[42:45]
	v_mfma_i32_16x16x64_i8 v[30:33], v[158:161], v[186:189], v[30:33]
	v_mfma_i32_16x16x64_i8 v[30:33], v[154:157], v[190:193], v[30:33]
	v_mfma_i32_16x16x64_i8 v[26:29], v[150:153], v[186:189], v[26:29]
	v_mfma_i32_16x16x64_i8 v[26:29], v[146:149], v[190:193], v[26:29]
	v_mfma_i32_16x16x64_i8 v[14:17], v[158:161], v[238:241], v[14:17]
	v_mfma_i32_16x16x64_i8 v[14:17], v[154:157], v[242:245], v[14:17]
	v_mfma_i32_16x16x64_i8 v[10:13], v[150:153], v[238:241], v[10:13]
	v_mfma_i32_16x16x64_i8 v[10:13], v[146:149], v[242:245], v[10:13]
	v_mfma_i32_16x16x64_i8 v[70:73], v[62:65], v[170:173], v[70:73]
	v_mfma_i32_16x16x64_i8 v[70:73], v[58:61], v[174:177], v[70:73]
	v_mfma_i32_16x16x64_i8 v[66:69], v[54:57], v[170:173], v[66:69]
	v_mfma_i32_16x16x64_i8 v[66:69], v[50:53], v[174:177], v[66:69]
	v_mfma_i32_16x16x64_i8 v[38:41], v[62:65], v[178:181], v[38:41]
	v_mfma_i32_16x16x64_i8 v[38:41], v[58:61], v[182:185], v[38:41]
	v_mfma_i32_16x16x64_i8 v[34:37], v[54:57], v[178:181], v[34:37]
	v_mfma_i32_16x16x64_i8 v[34:37], v[50:53], v[182:185], v[34:37]
	v_mfma_i32_16x16x64_i8 v[22:25], v[62:65], v[186:189], v[22:25]
	v_mfma_i32_16x16x64_i8 v[22:25], v[58:61], v[190:193], v[22:25]
	v_mfma_i32_16x16x64_i8 v[18:21], v[54:57], v[186:189], v[18:21]
	v_mfma_i32_16x16x64_i8 v[18:21], v[50:53], v[190:193], v[18:21]
	v_mfma_i32_16x16x64_i8 v[6:9], v[62:65], v[238:241], v[6:9]
	v_mfma_i32_16x16x64_i8 v[6:9], v[58:61], v[242:245], v[6:9]
	v_mfma_i32_16x16x64_i8 v[2:5], v[54:57], v[238:241], v[2:5]
	v_mfma_i32_16x16x64_i8 v[2:5], v[50:53], v[242:245], v[2:5]
	s_barrier
	ds_read_b128 v[50:53], v235
	ds_read_b128 v[54:57], v235 offset:1024
	ds_read_b128 v[58:61], v235 offset:2048
	ds_read_b128 v[62:65], v235 offset:3072
	ds_read_b128 v[146:149], v236
	ds_read_b128 v[150:153], v236 offset:1024
	ds_read_b128 v[154:157], v236 offset:2048
	ds_read_b128 v[158:161], v236 offset:3072
	s_add_u32 s40, s40, 0x80000
	s_addc_u32 s41, s41, 0
	s_mov_b32 m0, s43
	v_lshl_add_u64 v[246:247], s[40:41], 0, v[194:195]
	ds_read_b128 v[170:173], v226 offset:32768
	ds_read_b128 v[174:177], v226 offset:33792
	ds_read_b128 v[178:181], v226 offset:34816
	ds_read_b128 v[182:185], v226 offset:35840
	ds_read_b128 v[186:189], v226 offset:36864
	ds_read_b128 v[190:193], v226 offset:37888
	ds_read_b128 v[238:241], v226 offset:38912
	ds_read_b128 v[242:245], v226 offset:39936
	global_load_lds_dwordx4 v[246:247], off
	v_lshl_add_u64 v[246:247], s[40:41], 0, v[204:205]
	s_mov_b32 m0, s44
	s_nop 0
	global_load_lds_dwordx4 v[246:247], off
	s_waitcnt vmcnt(8)
	s_waitcnt lgkmcnt(0)
	s_barrier
	s_waitcnt lgkmcnt(0)
	v_mfma_i32_16x16x64_i8 v[142:145], v[50:53], v[170:173], v[142:145]
	v_mfma_i32_16x16x64_i8 v[142:145], v[54:57], v[174:177], v[142:145]
	v_mfma_i32_16x16x64_i8 v[138:141], v[58:61], v[170:173], v[138:141]
	v_mfma_i32_16x16x64_i8 v[138:141], v[62:65], v[174:177], v[138:141]
	v_mfma_i32_16x16x64_i8 v[126:129], v[50:53], v[178:181], v[126:129]
	v_mfma_i32_16x16x64_i8 v[126:129], v[54:57], v[182:185], v[126:129]
	v_mfma_i32_16x16x64_i8 v[122:125], v[58:61], v[178:181], v[122:125]
	v_mfma_i32_16x16x64_i8 v[122:125], v[62:65], v[182:185], v[122:125]
	v_mfma_i32_16x16x64_i8 v[110:113], v[50:53], v[186:189], v[110:113]
	v_mfma_i32_16x16x64_i8 v[110:113], v[54:57], v[190:193], v[110:113]
	v_mfma_i32_16x16x64_i8 v[106:109], v[58:61], v[186:189], v[106:109]
	v_mfma_i32_16x16x64_i8 v[106:109], v[62:65], v[190:193], v[106:109]
	v_mfma_i32_16x16x64_i8 v[94:97], v[50:53], v[238:241], v[94:97]
	v_mfma_i32_16x16x64_i8 v[94:97], v[54:57], v[242:245], v[94:97]
	v_mfma_i32_16x16x64_i8 v[90:93], v[58:61], v[238:241], v[90:93]
	v_mfma_i32_16x16x64_i8 v[90:93], v[62:65], v[242:245], v[90:93]
	v_mfma_i32_16x16x64_i8 v[134:137], v[146:149], v[170:173], v[134:137]
	v_mfma_i32_16x16x64_i8 v[134:137], v[150:153], v[174:177], v[134:137]
	v_mfma_i32_16x16x64_i8 v[130:133], v[154:157], v[170:173], v[130:133]
	v_mfma_i32_16x16x64_i8 v[130:133], v[158:161], v[174:177], v[130:133]
	v_mfma_i32_16x16x64_i8 v[118:121], v[146:149], v[178:181], v[118:121]
	v_mfma_i32_16x16x64_i8 v[118:121], v[150:153], v[182:185], v[118:121]
	v_mfma_i32_16x16x64_i8 v[114:117], v[154:157], v[178:181], v[114:117]
	v_mfma_i32_16x16x64_i8 v[114:117], v[158:161], v[182:185], v[114:117]
	v_mfma_i32_16x16x64_i8 v[102:105], v[146:149], v[186:189], v[102:105]
	v_mfma_i32_16x16x64_i8 v[102:105], v[150:153], v[190:193], v[102:105]
	v_mfma_i32_16x16x64_i8 v[98:101], v[154:157], v[186:189], v[98:101]
	v_mfma_i32_16x16x64_i8 v[98:101], v[158:161], v[190:193], v[98:101]
	v_mfma_i32_16x16x64_i8 v[86:89], v[146:149], v[238:241], v[86:89]
	v_mfma_i32_16x16x64_i8 v[86:89], v[150:153], v[242:245], v[86:89]
	v_mfma_i32_16x16x64_i8 v[82:85], v[154:157], v[238:241], v[82:85]
	v_mfma_i32_16x16x64_i8 v[82:85], v[158:161], v[242:245], v[82:85]
	s_barrier
	s_mov_b32 m0, s72
	v_lshl_add_u64 v[162:163], v[162:163], 0, s[6:7]
	s_add_u32 s36, s36, 0x80080
	ds_read_b128 v[170:173], v226 offset:49152
	ds_read_b128 v[174:177], v226 offset:50176
	ds_read_b128 v[178:181], v226 offset:51200
	ds_read_b128 v[182:185], v226 offset:52224
	ds_read_b128 v[186:189], v226 offset:53248
	ds_read_b128 v[190:193], v226 offset:54272
	ds_read_b128 v[238:241], v226 offset:55296
	ds_read_b128 v[242:245], v226 offset:56320
	global_load_lds_dwordx4 v[162:163], off
	v_lshl_add_u64 v[162:163], v[164:165], 0, s[6:7]
	s_mov_b32 m0, s73
	s_addc_u32 s37, s37, 0
	global_load_lds_dwordx4 v[162:163], off
	v_lshl_add_u64 v[162:163], s[36:37], 0, v[202:203]
	s_mov_b32 m0, s74
	s_nop 0
	global_load_lds_dwordx4 v[162:163], off
	v_lshl_add_u64 v[162:163], s[36:37], 0, v[206:207]
	s_mov_b32 m0, s75
	s_nop 0
	global_load_lds_dwordx4 v[162:163], off
	v_lshl_add_u64 v[162:163], v[166:167], 0, s[6:7]
	s_mov_b32 m0, s51
	s_nop 0
	global_load_lds_dwordx4 v[162:163], off
	v_lshl_add_u64 v[162:163], v[168:169], 0, s[6:7]
	s_mov_b32 m0, s53
	s_nop 0
	global_load_lds_dwordx4 v[162:163], off
	s_waitcnt vmcnt(8)
	s_waitcnt lgkmcnt(0)
	s_barrier
	s_waitcnt lgkmcnt(0)
	v_mfma_i32_16x16x64_i8 v[78:81], v[50:53], v[170:173], v[78:81]
	v_mfma_i32_16x16x64_i8 v[78:81], v[54:57], v[174:177], v[78:81]
	v_mfma_i32_16x16x64_i8 v[74:77], v[58:61], v[170:173], v[74:77]
	v_mfma_i32_16x16x64_i8 v[74:77], v[62:65], v[174:177], v[74:77]
	v_mfma_i32_16x16x64_i8 v[46:49], v[50:53], v[178:181], v[46:49]
	v_mfma_i32_16x16x64_i8 v[46:49], v[54:57], v[182:185], v[46:49]
	v_mfma_i32_16x16x64_i8 v[42:45], v[58:61], v[178:181], v[42:45]
	v_mfma_i32_16x16x64_i8 v[42:45], v[62:65], v[182:185], v[42:45]
	v_mfma_i32_16x16x64_i8 v[30:33], v[50:53], v[186:189], v[30:33]
	v_mfma_i32_16x16x64_i8 v[30:33], v[54:57], v[190:193], v[30:33]
	v_mfma_i32_16x16x64_i8 v[26:29], v[58:61], v[186:189], v[26:29]
	v_mfma_i32_16x16x64_i8 v[26:29], v[62:65], v[190:193], v[26:29]
	v_mfma_i32_16x16x64_i8 v[14:17], v[50:53], v[238:241], v[14:17]
	v_mfma_i32_16x16x64_i8 v[14:17], v[54:57], v[242:245], v[14:17]
	v_mfma_i32_16x16x64_i8 v[10:13], v[58:61], v[238:241], v[10:13]
	v_mfma_i32_16x16x64_i8 v[10:13], v[62:65], v[242:245], v[10:13]
	v_mfma_i32_16x16x64_i8 v[70:73], v[146:149], v[170:173], v[70:73]
	v_mfma_i32_16x16x64_i8 v[70:73], v[150:153], v[174:177], v[70:73]
	v_mfma_i32_16x16x64_i8 v[66:69], v[154:157], v[170:173], v[66:69]
	v_mfma_i32_16x16x64_i8 v[66:69], v[158:161], v[174:177], v[66:69]
	v_mfma_i32_16x16x64_i8 v[38:41], v[146:149], v[178:181], v[38:41]
	v_mfma_i32_16x16x64_i8 v[38:41], v[150:153], v[182:185], v[38:41]
	v_mfma_i32_16x16x64_i8 v[34:37], v[154:157], v[178:181], v[34:37]
	v_mfma_i32_16x16x64_i8 v[34:37], v[158:161], v[182:185], v[34:37]
	v_mfma_i32_16x16x64_i8 v[22:25], v[146:149], v[186:189], v[22:25]
	v_mfma_i32_16x16x64_i8 v[22:25], v[150:153], v[190:193], v[22:25]
	v_mfma_i32_16x16x64_i8 v[18:21], v[154:157], v[186:189], v[18:21]
	v_mfma_i32_16x16x64_i8 v[18:21], v[158:161], v[190:193], v[18:21]
	v_mfma_i32_16x16x64_i8 v[6:9], v[146:149], v[238:241], v[6:9]
	v_mfma_i32_16x16x64_i8 v[6:9], v[150:153], v[242:245], v[6:9]
	v_mfma_i32_16x16x64_i8 v[2:5], v[154:157], v[238:241], v[2:5]
	v_mfma_i32_16x16x64_i8 v[2:5], v[158:161], v[242:245], v[2:5]
	s_add_i32 s33, s33, 2
	s_add_u32 s38, s38, 0x100
	s_addc_u32 s39, s39, 0
	s_add_u32 s25, s25, 0x100
	s_addc_u32 s29, s29, 0
	s_cmp_gt_u32 s33, 29
	s_barrier
	s_cbranch_scc0 .LBB0_740
	s_nop 15
	s_nop 15
	s_and_b64 vcc, exec, s[8:9]
	s_cbranch_vccz .LBB0_743
	s_barrier

.LBB0_746:
	ds_read_b128 v[158:161], v227
	ds_read_b128 v[154:157], v227 offset:1024
	ds_read_b128 v[150:153], v227 offset:2048
	ds_read_b128 v[146:149], v227 offset:3072
	ds_read_b128 v[142:145], v233
	ds_read_b128 v[138:141], v233 offset:1024
	ds_read_b128 v[134:137], v233 offset:2048
	ds_read_b128 v[130:133], v233 offset:3072
	s_add_u32 s38, s29, s36
	s_addc_u32 s39, s33, s37
	s_add_u32 s38, s38, 0x3d000100
	s_addc_u32 s39, s39, 0
	s_add_u32 s81, s25, s36
	s_addc_u32 s82, s79, s37
	s_cmpk_eq_i32 s36, 0x700
	s_cselect_b32 s41, s1, s39
	s_cselect_b32 s40, s0, s38
	s_cselect_b32 s39, s15, s82
	s_cselect_b32 s38, s14, s81
	s_mov_b32 m0, s66
	v_lshl_add_u64 v[242:243], v[162:163], 0, s[36:37]
	ds_read_b128 v[166:169], v226
	ds_read_b128 v[170:173], v226 offset:1024
	ds_read_b128 v[174:177], v226 offset:2048
	ds_read_b128 v[178:181], v226 offset:3072
	ds_read_b128 v[182:185], v226 offset:4096
	ds_read_b128 v[186:189], v226 offset:5120
	ds_read_b128 v[190:193], v226 offset:6144
	ds_read_b128 v[238:241], v226 offset:7168
	global_load_lds_dwordx4 v[242:243], off
	v_lshl_add_u64 v[242:243], v[164:165], 0, s[36:37]
	s_mov_b32 m0, s67
	s_nop 0
	global_load_lds_dwordx4 v[242:243], off
	s_waitcnt vmcnt(8)
	s_waitcnt lgkmcnt(0)
	s_barrier
	s_waitcnt lgkmcnt(0)
	v_mfma_i32_16x16x64_i8 v[30:33], v[158:161], v[166:169], v[30:33]
	v_mfma_i32_16x16x64_i8 v[30:33], v[154:157], v[170:173], v[30:33]
	v_mfma_i32_16x16x64_i8 v[26:29], v[150:153], v[166:169], v[26:29]
	v_mfma_i32_16x16x64_i8 v[26:29], v[146:149], v[170:173], v[26:29]
	v_mfma_i32_16x16x64_i8 v[46:49], v[158:161], v[174:177], v[46:49]
	v_mfma_i32_16x16x64_i8 v[46:49], v[154:157], v[178:181], v[46:49]
	v_mfma_i32_16x16x64_i8 v[42:45], v[150:153], v[174:177], v[42:45]
	v_mfma_i32_16x16x64_i8 v[42:45], v[146:149], v[178:181], v[42:45]
	v_mfma_i32_16x16x64_i8 v[74:77], v[158:161], v[182:185], v[74:77]
	v_mfma_i32_16x16x64_i8 v[74:77], v[154:157], v[186:189], v[74:77]
	v_mfma_i32_16x16x64_i8 v[70:73], v[150:153], v[182:185], v[70:73]
	v_mfma_i32_16x16x64_i8 v[70:73], v[146:149], v[186:189], v[70:73]
	v_mfma_i32_16x16x64_i8 v[94:97], v[158:161], v[190:193], v[94:97]
	v_mfma_i32_16x16x64_i8 v[94:97], v[154:157], v[238:241], v[94:97]
	v_mfma_i32_16x16x64_i8 v[90:93], v[150:153], v[190:193], v[90:93]
	v_mfma_i32_16x16x64_i8 v[90:93], v[146:149], v[238:241], v[90:93]
	v_mfma_i32_16x16x64_i8 v[38:41], v[142:145], v[166:169], v[38:41]
	v_mfma_i32_16x16x64_i8 v[38:41], v[138:141], v[170:173], v[38:41]
	v_mfma_i32_16x16x64_i8 v[34:37], v[134:137], v[166:169], v[34:37]
	v_mfma_i32_16x16x64_i8 v[34:37], v[130:133], v[170:173], v[34:37]
	v_mfma_i32_16x16x64_i8 v[58:61], v[142:145], v[174:177], v[58:61]
	v_mfma_i32_16x16x64_i8 v[58:61], v[138:141], v[178:181], v[58:61]
	v_mfma_i32_16x16x64_i8 v[54:57], v[134:137], v[174:177], v[54:57]
	v_mfma_i32_16x16x64_i8 v[54:57], v[130:133], v[178:181], v[54:57]
	v_mfma_i32_16x16x64_i8 v[86:89], v[142:145], v[182:185], v[86:89]
	v_mfma_i32_16x16x64_i8 v[86:89], v[138:141], v[186:189], v[86:89]
	v_mfma_i32_16x16x64_i8 v[82:85], v[134:137], v[182:185], v[82:85]
	v_mfma_i32_16x16x64_i8 v[82:85], v[130:133], v[186:189], v[82:85]
	v_mfma_i32_16x16x64_i8 v[102:105], v[142:145], v[190:193], v[102:105]
	v_mfma_i32_16x16x64_i8 v[102:105], v[138:141], v[238:241], v[102:105]
	v_mfma_i32_16x16x64_i8 v[98:101], v[134:137], v[190:193], v[98:101]
	v_mfma_i32_16x16x64_i8 v[98:101], v[130:133], v[238:241], v[98:101]
	s_barrier
	s_mov_b32 m0, s68
	v_lshl_add_u64 v[166:167], s[38:39], 0, v[202:203]
	s_add_u32 s82, s38, 0x80000
	ds_read_b128 v[174:177], v226 offset:16384
	ds_read_b128 v[178:181], v226 offset:17408
	ds_read_b128 v[182:185], v226 offset:18432
	ds_read_b128 v[186:189], v226 offset:19456
	ds_read_b128 v[190:193], v226 offset:20480
	ds_read_b128 v[238:241], v226 offset:21504
	ds_read_b128 v[242:245], v226 offset:22528
	ds_read_b128 v[246:249], v226 offset:23552
	global_load_lds_dwordx4 v[166:167], off
	v_lshl_add_u64 v[168:169], s[38:39], 0, v[206:207]
	s_mov_b32 m0, s69
	s_addc_u32 s83, s39, 0
	global_load_lds_dwordx4 v[168:169], off
	v_lshl_add_u64 v[170:171], s[82:83], 0, v[202:203]
	s_mov_b32 m0, s70
	v_lshl_add_u64 v[172:173], s[40:41], 0, v[204:205]
	global_load_lds_dwordx4 v[170:171], off
	v_lshl_add_u64 v[170:171], s[82:83], 0, v[206:207]
	s_mov_b32 m0, s71
	s_nop 0
	global_load_lds_dwordx4 v[170:171], off
	v_lshl_add_u64 v[170:171], s[40:41], 0, v[194:195]
	s_mov_b32 m0, s23
	s_nop 0
	global_load_lds_dwordx4 v[170:171], off
	s_mov_b32 m0, s42
	s_nop 0
	global_load_lds_dwordx4 v[172:173], off
	s_waitcnt vmcnt(8)
	s_waitcnt lgkmcnt(0)
	s_barrier
	s_waitcnt lgkmcnt(0)
	v_mfma_i32_16x16x64_i8 v[110:113], v[158:161], v[174:177], v[110:113]
	v_mfma_i32_16x16x64_i8 v[110:113], v[154:157], v[178:181], v[110:113]
	v_mfma_i32_16x16x64_i8 v[106:109], v[150:153], v[174:177], v[106:109]
	v_mfma_i32_16x16x64_i8 v[106:109], v[146:149], v[178:181], v[106:109]
	v_mfma_i32_16x16x64_i8 v[126:129], v[158:161], v[182:185], v[126:129]
	v_mfma_i32_16x16x64_i8 v[126:129], v[154:157], v[186:189], v[126:129]
	v_mfma_i32_16x16x64_i8 v[118:121], v[150:153], v[182:185], v[118:121]
	v_mfma_i32_16x16x64_i8 v[118:121], v[146:149], v[186:189], v[118:121]
	v_mfma_i32_16x16x64_i8 v[62:65], v[158:161], v[190:193], v[62:65]
	v_mfma_i32_16x16x64_i8 v[62:65], v[154:157], v[238:241], v[62:65]
	v_mfma_i32_16x16x64_i8 v[50:53], v[150:153], v[190:193], v[50:53]
	v_mfma_i32_16x16x64_i8 v[50:53], v[146:149], v[238:241], v[50:53]
	v_mfma_i32_16x16x64_i8 v[14:17], v[158:161], v[242:245], v[14:17]
	v_mfma_i32_16x16x64_i8 v[14:17], v[154:157], v[246:249], v[14:17]
	v_mfma_i32_16x16x64_i8 v[10:13], v[150:153], v[242:245], v[10:13]
	v_mfma_i32_16x16x64_i8 v[10:13], v[146:149], v[246:249], v[10:13]
	v_mfma_i32_16x16x64_i8 v[122:125], v[142:145], v[174:177], v[122:125]
	v_mfma_i32_16x16x64_i8 v[122:125], v[138:141], v[178:181], v[122:125]
	v_mfma_i32_16x16x64_i8 v[114:117], v[134:137], v[174:177], v[114:117]
	v_mfma_i32_16x16x64_i8 v[114:117], v[130:133], v[178:181], v[114:117]
	v_mfma_i32_16x16x64_i8 v[78:81], v[142:145], v[182:185], v[78:81]
	v_mfma_i32_16x16x64_i8 v[78:81], v[138:141], v[186:189], v[78:81]
	v_mfma_i32_16x16x64_i8 v[66:69], v[134:137], v[182:185], v[66:69]
	v_mfma_i32_16x16x64_i8 v[66:69], v[130:133], v[186:189], v[66:69]
	v_mfma_i32_16x16x64_i8 v[22:25], v[142:145], v[190:193], v[22:25]
	v_mfma_i32_16x16x64_i8 v[22:25], v[138:141], v[238:241], v[22:25]
	v_mfma_i32_16x16x64_i8 v[18:21], v[134:137], v[190:193], v[18:21]
	v_mfma_i32_16x16x64_i8 v[18:21], v[130:133], v[238:241], v[18:21]
	v_mfma_i32_16x16x64_i8 v[6:9], v[142:145], v[242:245], v[6:9]
	v_mfma_i32_16x16x64_i8 v[6:9], v[138:141], v[246:249], v[6:9]
	v_mfma_i32_16x16x64_i8 v[2:5], v[134:137], v[242:245], v[2:5]
	v_mfma_i32_16x16x64_i8 v[2:5], v[130:133], v[246:249], v[2:5]
	s_barrier
	ds_read_b128 v[130:133], v235
	ds_read_b128 v[134:137], v235 offset:1024
	ds_read_b128 v[138:141], v235 offset:2048
	ds_read_b128 v[142:145], v235 offset:3072
	ds_read_b128 v[146:149], v236
	ds_read_b128 v[150:153], v236 offset:1024
	ds_read_b128 v[154:157], v236 offset:2048
	ds_read_b128 v[158:161], v236 offset:3072
	s_add_u32 s40, s40, 0x80000
	s_addc_u32 s41, s41, 0
	s_mov_b32 m0, s43
	v_lshl_add_u64 v[250:251], s[40:41], 0, v[194:195]
	ds_read_b128 v[174:177], v226 offset:32768
	ds_read_b128 v[178:181], v226 offset:33792
	ds_read_b128 v[182:185], v226 offset:34816
	ds_read_b128 v[186:189], v226 offset:35840
	ds_read_b128 v[190:193], v226 offset:36864
	ds_read_b128 v[238:241], v226 offset:37888
	ds_read_b128 v[242:245], v226 offset:38912
	ds_read_b128 v[246:249], v226 offset:39936
	global_load_lds_dwordx4 v[250:251], off
	v_lshl_add_u64 v[250:251], s[40:41], 0, v[204:205]
	s_mov_b32 m0, s44
	s_nop 0
	global_load_lds_dwordx4 v[250:251], off
	s_waitcnt vmcnt(8)
	s_waitcnt lgkmcnt(0)
	s_barrier
	s_waitcnt lgkmcnt(0)
	v_mfma_i32_16x16x64_i8 v[30:33], v[130:133], v[174:177], v[30:33]
	v_mfma_i32_16x16x64_i8 v[30:33], v[134:137], v[178:181], v[30:33]
	v_mfma_i32_16x16x64_i8 v[26:29], v[138:141], v[174:177], v[26:29]
	v_mfma_i32_16x16x64_i8 v[26:29], v[142:145], v[178:181], v[26:29]
	v_mfma_i32_16x16x64_i8 v[46:49], v[130:133], v[182:185], v[46:49]
	v_mfma_i32_16x16x64_i8 v[46:49], v[134:137], v[186:189], v[46:49]
	v_mfma_i32_16x16x64_i8 v[42:45], v[138:141], v[182:185], v[42:45]
	v_mfma_i32_16x16x64_i8 v[42:45], v[142:145], v[186:189], v[42:45]
	v_mfma_i32_16x16x64_i8 v[74:77], v[130:133], v[190:193], v[74:77]
	v_mfma_i32_16x16x64_i8 v[74:77], v[134:137], v[238:241], v[74:77]
	v_mfma_i32_16x16x64_i8 v[70:73], v[138:141], v[190:193], v[70:73]
	v_mfma_i32_16x16x64_i8 v[70:73], v[142:145], v[238:241], v[70:73]
	v_mfma_i32_16x16x64_i8 v[94:97], v[130:133], v[242:245], v[94:97]
	v_mfma_i32_16x16x64_i8 v[94:97], v[134:137], v[246:249], v[94:97]
	v_mfma_i32_16x16x64_i8 v[90:93], v[138:141], v[242:245], v[90:93]
	v_mfma_i32_16x16x64_i8 v[90:93], v[142:145], v[246:249], v[90:93]
	v_mfma_i32_16x16x64_i8 v[38:41], v[146:149], v[174:177], v[38:41]
	v_mfma_i32_16x16x64_i8 v[38:41], v[150:153], v[178:181], v[38:41]
	v_mfma_i32_16x16x64_i8 v[34:37], v[154:157], v[174:177], v[34:37]
	v_mfma_i32_16x16x64_i8 v[34:37], v[158:161], v[178:181], v[34:37]
	v_mfma_i32_16x16x64_i8 v[58:61], v[146:149], v[182:185], v[58:61]
	v_mfma_i32_16x16x64_i8 v[58:61], v[150:153], v[186:189], v[58:61]
	v_mfma_i32_16x16x64_i8 v[54:57], v[154:157], v[182:185], v[54:57]
	v_mfma_i32_16x16x64_i8 v[54:57], v[158:161], v[186:189], v[54:57]
	v_mfma_i32_16x16x64_i8 v[86:89], v[146:149], v[190:193], v[86:89]
	v_mfma_i32_16x16x64_i8 v[86:89], v[150:153], v[238:241], v[86:89]
	v_mfma_i32_16x16x64_i8 v[82:85], v[154:157], v[190:193], v[82:85]
	v_mfma_i32_16x16x64_i8 v[82:85], v[158:161], v[238:241], v[82:85]
	v_mfma_i32_16x16x64_i8 v[102:105], v[146:149], v[242:245], v[102:105]
	v_mfma_i32_16x16x64_i8 v[102:105], v[150:153], v[246:249], v[102:105]
	v_mfma_i32_16x16x64_i8 v[98:101], v[154:157], v[242:245], v[98:101]
	v_mfma_i32_16x16x64_i8 v[98:101], v[158:161], v[246:249], v[98:101]
	s_barrier
	s_mov_b32 m0, s72
	v_lshl_add_u64 v[166:167], v[166:167], 0, s[6:7]
	s_add_u32 s38, s38, 0x80080
	ds_read_b128 v[174:177], v226 offset:49152
	ds_read_b128 v[178:181], v226 offset:50176
	ds_read_b128 v[182:185], v226 offset:51200
	ds_read_b128 v[186:189], v226 offset:52224
	ds_read_b128 v[190:193], v226 offset:53248
	ds_read_b128 v[238:241], v226 offset:54272
	ds_read_b128 v[242:245], v226 offset:55296
	ds_read_b128 v[246:249], v226 offset:56320
	global_load_lds_dwordx4 v[166:167], off
	v_lshl_add_u64 v[166:167], v[168:169], 0, s[6:7]
	s_mov_b32 m0, s73
	s_addc_u32 s39, s39, 0
	global_load_lds_dwordx4 v[166:167], off
	v_lshl_add_u64 v[166:167], s[38:39], 0, v[202:203]
	s_mov_b32 m0, s74
	s_nop 0
	global_load_lds_dwordx4 v[166:167], off
	v_lshl_add_u64 v[166:167], s[38:39], 0, v[206:207]
	s_mov_b32 m0, s75
	s_nop 0
	global_load_lds_dwordx4 v[166:167], off
	v_lshl_add_u64 v[166:167], v[170:171], 0, s[6:7]
	s_mov_b32 m0, s51
	s_nop 0
	global_load_lds_dwordx4 v[166:167], off
	v_lshl_add_u64 v[166:167], v[172:173], 0, s[6:7]
	s_mov_b32 m0, s53
	s_nop 0
	global_load_lds_dwordx4 v[166:167], off
	s_waitcnt vmcnt(8)
	s_waitcnt lgkmcnt(0)
	s_barrier
	s_waitcnt lgkmcnt(0)
	v_mfma_i32_16x16x64_i8 v[110:113], v[130:133], v[174:177], v[110:113]
	v_mfma_i32_16x16x64_i8 v[110:113], v[134:137], v[178:181], v[110:113]
	v_mfma_i32_16x16x64_i8 v[106:109], v[138:141], v[174:177], v[106:109]
	v_mfma_i32_16x16x64_i8 v[106:109], v[142:145], v[178:181], v[106:109]
	v_mfma_i32_16x16x64_i8 v[126:129], v[130:133], v[182:185], v[126:129]
	v_mfma_i32_16x16x64_i8 v[126:129], v[134:137], v[186:189], v[126:129]
	v_mfma_i32_16x16x64_i8 v[118:121], v[138:141], v[182:185], v[118:121]
	v_mfma_i32_16x16x64_i8 v[118:121], v[142:145], v[186:189], v[118:121]
	v_mfma_i32_16x16x64_i8 v[62:65], v[130:133], v[190:193], v[62:65]
	v_mfma_i32_16x16x64_i8 v[62:65], v[134:137], v[238:241], v[62:65]
	v_mfma_i32_16x16x64_i8 v[50:53], v[138:141], v[190:193], v[50:53]
	v_mfma_i32_16x16x64_i8 v[50:53], v[142:145], v[238:241], v[50:53]
	v_mfma_i32_16x16x64_i8 v[14:17], v[130:133], v[242:245], v[14:17]
	v_mfma_i32_16x16x64_i8 v[14:17], v[134:137], v[246:249], v[14:17]
	v_mfma_i32_16x16x64_i8 v[10:13], v[138:141], v[242:245], v[10:13]
	v_mfma_i32_16x16x64_i8 v[10:13], v[142:145], v[246:249], v[10:13]
	v_mfma_i32_16x16x64_i8 v[122:125], v[146:149], v[174:177], v[122:125]
	v_mfma_i32_16x16x64_i8 v[122:125], v[150:153], v[178:181], v[122:125]
	v_mfma_i32_16x16x64_i8 v[114:117], v[154:157], v[174:177], v[114:117]
	v_mfma_i32_16x16x64_i8 v[114:117], v[158:161], v[178:181], v[114:117]
	v_mfma_i32_16x16x64_i8 v[78:81], v[146:149], v[182:185], v[78:81]
	v_mfma_i32_16x16x64_i8 v[78:81], v[150:153], v[186:189], v[78:81]
	v_mfma_i32_16x16x64_i8 v[66:69], v[154:157], v[182:185], v[66:69]
	v_mfma_i32_16x16x64_i8 v[66:69], v[158:161], v[186:189], v[66:69]
	v_mfma_i32_16x16x64_i8 v[22:25], v[146:149], v[190:193], v[22:25]
	v_mfma_i32_16x16x64_i8 v[22:25], v[150:153], v[238:241], v[22:25]
	v_mfma_i32_16x16x64_i8 v[18:21], v[154:157], v[190:193], v[18:21]
	v_mfma_i32_16x16x64_i8 v[18:21], v[158:161], v[238:241], v[18:21]
	v_mfma_i32_16x16x64_i8 v[6:9], v[146:149], v[242:245], v[6:9]
	v_mfma_i32_16x16x64_i8 v[6:9], v[150:153], v[246:249], v[6:9]
	v_mfma_i32_16x16x64_i8 v[2:5], v[154:157], v[242:245], v[2:5]
	v_mfma_i32_16x16x64_i8 v[2:5], v[158:161], v[246:249], v[2:5]
	s_add_i32 s80, s80, 2
	s_add_u32 s36, s36, 0x100
	s_addc_u32 s37, s37, 0
	s_cmp_gt_u32 s80, 13
	s_barrier
	s_cbranch_scc0 .LBB0_746
	s_nop 15
	s_nop 15
	s_and_b64 vcc, exec, s[8:9]
	s_cbranch_vccz .LBB0_749
	s_barrier

.LBB0_752:
	ds_read_b128 v[134:137], v227
	ds_read_b128 v[138:141], v227 offset:1024
	ds_read_b128 v[142:145], v227 offset:2048
	ds_read_b128 v[146:149], v227 offset:3072
	ds_read_b128 v[150:153], v233
	ds_read_b128 v[154:157], v233 offset:1024
	ds_read_b128 v[158:161], v233 offset:2048
	ds_read_b128 v[162:165], v233 offset:3072
	s_add_u32 s30, s29, s2
	s_addc_u32 s31, s33, s3
	s_add_u32 s30, s30, 0x200100
	s_addc_u32 s31, s31, 0
	s_add_u32 s77, s25, s2
	s_addc_u32 s78, s40, s3
	s_cmpk_eq_i32 s2, 0xf00
	s_cselect_b32 s35, s0, s31
	s_cselect_b32 s34, s1, s30
	s_cselect_b32 s31, s14, s78
	s_cselect_b32 s30, s15, s77
	s_mov_b32 m0, s66
	v_lshl_add_u64 v[242:243], v[130:131], 0, s[2:3]
	ds_read_b128 v[166:169], v226
	ds_read_b128 v[170:173], v226 offset:1024
	ds_read_b128 v[174:177], v226 offset:2048
	ds_read_b128 v[178:181], v226 offset:3072
	ds_read_b128 v[182:185], v226 offset:4096
	ds_read_b128 v[186:189], v226 offset:5120
	ds_read_b128 v[190:193], v226 offset:6144
	ds_read_b128 v[238:241], v226 offset:7168
	global_load_lds_dwordx4 v[242:243], off
	v_lshl_add_u64 v[242:243], v[132:133], 0, s[2:3]
	s_mov_b32 m0, s67
	s_nop 0
	global_load_lds_dwordx4 v[242:243], off
	s_waitcnt vmcnt(8)
	s_waitcnt lgkmcnt(0)
	s_barrier
	s_waitcnt lgkmcnt(0)
	v_mfma_f32_16x16x32_bf16 v[26:29], v[134:137], v[166:169], v[26:29]
	v_mfma_f32_16x16x32_bf16 v[30:33], v[142:145], v[166:169], v[30:33]
	v_mfma_f32_16x16x32_bf16 v[42:45], v[134:137], v[174:177], v[42:45]
	v_mfma_f32_16x16x32_bf16 v[46:49], v[142:145], v[174:177], v[46:49]
	v_mfma_f32_16x16x32_bf16 v[70:73], v[134:137], v[182:185], v[70:73]
	v_mfma_f32_16x16x32_bf16 v[74:77], v[142:145], v[182:185], v[74:77]
	v_mfma_f32_16x16x32_bf16 v[90:93], v[134:137], v[190:193], v[90:93]
	v_mfma_f32_16x16x32_bf16 v[94:97], v[142:145], v[190:193], v[94:97]
	v_mfma_f32_16x16x32_bf16 v[26:29], v[138:141], v[170:173], v[26:29]
	v_mfma_f32_16x16x32_bf16 v[30:33], v[146:149], v[170:173], v[30:33]
	v_mfma_f32_16x16x32_bf16 v[42:45], v[138:141], v[178:181], v[42:45]
	v_mfma_f32_16x16x32_bf16 v[46:49], v[146:149], v[178:181], v[46:49]
	v_mfma_f32_16x16x32_bf16 v[70:73], v[138:141], v[186:189], v[70:73]
	v_mfma_f32_16x16x32_bf16 v[74:77], v[146:149], v[186:189], v[74:77]
	v_mfma_f32_16x16x32_bf16 v[90:93], v[138:141], v[238:241], v[90:93]
	v_mfma_f32_16x16x32_bf16 v[94:97], v[146:149], v[238:241], v[94:97]
	v_mfma_f32_16x16x32_bf16 v[34:37], v[150:153], v[166:169], v[34:37]
	v_mfma_f32_16x16x32_bf16 v[38:41], v[158:161], v[166:169], v[38:41]
	v_mfma_f32_16x16x32_bf16 v[54:57], v[150:153], v[174:177], v[54:57]
	v_mfma_f32_16x16x32_bf16 v[58:61], v[158:161], v[174:177], v[58:61]
	v_mfma_f32_16x16x32_bf16 v[82:85], v[150:153], v[182:185], v[82:85]
	v_mfma_f32_16x16x32_bf16 v[86:89], v[158:161], v[182:185], v[86:89]
	v_mfma_f32_16x16x32_bf16 v[98:101], v[150:153], v[190:193], v[98:101]
	v_mfma_f32_16x16x32_bf16 v[102:105], v[158:161], v[190:193], v[102:105]
	v_mfma_f32_16x16x32_bf16 v[34:37], v[154:157], v[170:173], v[34:37]
	v_mfma_f32_16x16x32_bf16 v[38:41], v[162:165], v[170:173], v[38:41]
	v_mfma_f32_16x16x32_bf16 v[54:57], v[154:157], v[178:181], v[54:57]
	v_mfma_f32_16x16x32_bf16 v[58:61], v[162:165], v[178:181], v[58:61]
	v_mfma_f32_16x16x32_bf16 v[82:85], v[154:157], v[186:189], v[82:85]
	v_mfma_f32_16x16x32_bf16 v[86:89], v[162:165], v[186:189], v[86:89]
	v_mfma_f32_16x16x32_bf16 v[98:101], v[154:157], v[238:241], v[98:101]
	v_mfma_f32_16x16x32_bf16 v[102:105], v[162:165], v[238:241], v[102:105]
	s_barrier
	s_mov_b32 m0, s68
	v_lshl_add_u64 v[242:243], s[30:31], 0, v[202:203]
	s_add_u32 s78, s30, 0x80000
	ds_read_b128 v[166:169], v226 offset:16384
	ds_read_b128 v[170:173], v226 offset:17408
	ds_read_b128 v[174:177], v226 offset:18432
	ds_read_b128 v[178:181], v226 offset:19456
	ds_read_b128 v[182:185], v226 offset:20480
	ds_read_b128 v[186:189], v226 offset:21504
	ds_read_b128 v[190:193], v226 offset:22528
	ds_read_b128 v[238:241], v226 offset:23552
	global_load_lds_dwordx4 v[242:243], off
	v_lshl_add_u64 v[244:245], s[30:31], 0, v[206:207]
	s_mov_b32 m0, s69
	s_addc_u32 s79, s31, 0
	global_load_lds_dwordx4 v[244:245], off
	v_lshl_add_u64 v[246:247], s[78:79], 0, v[202:203]
	s_mov_b32 m0, s70
	v_lshl_add_u64 v[248:249], s[34:35], 0, v[204:205]
	global_load_lds_dwordx4 v[246:247], off
	v_lshl_add_u64 v[246:247], s[78:79], 0, v[206:207]
	s_mov_b32 m0, s71
	s_nop 0
	global_load_lds_dwordx4 v[246:247], off
	v_lshl_add_u64 v[246:247], s[34:35], 0, v[194:195]
	s_mov_b32 m0, s23
	s_nop 0
	global_load_lds_dwordx4 v[246:247], off
	s_mov_b32 m0, s42
	s_nop 0
	global_load_lds_dwordx4 v[248:249], off
	s_waitcnt vmcnt(8)
	s_waitcnt lgkmcnt(0)
	s_barrier
	s_waitcnt lgkmcnt(0)
	v_mfma_f32_16x16x32_bf16 v[106:109], v[134:137], v[166:169], v[106:109]
	v_mfma_f32_16x16x32_bf16 v[110:113], v[142:145], v[166:169], v[110:113]
	v_mfma_f32_16x16x32_bf16 v[118:121], v[134:137], v[174:177], v[118:121]
	v_mfma_f32_16x16x32_bf16 v[126:129], v[142:145], v[174:177], v[126:129]
	v_mfma_f32_16x16x32_bf16 v[50:53], v[134:137], v[182:185], v[50:53]
	v_mfma_f32_16x16x32_bf16 v[62:65], v[142:145], v[182:185], v[62:65]
	v_mfma_f32_16x16x32_bf16 v[10:13], v[134:137], v[190:193], v[10:13]
	v_mfma_f32_16x16x32_bf16 v[14:17], v[142:145], v[190:193], v[14:17]
	v_mfma_f32_16x16x32_bf16 v[106:109], v[138:141], v[170:173], v[106:109]
	v_mfma_f32_16x16x32_bf16 v[110:113], v[146:149], v[170:173], v[110:113]
	v_mfma_f32_16x16x32_bf16 v[118:121], v[138:141], v[178:181], v[118:121]
	v_mfma_f32_16x16x32_bf16 v[126:129], v[146:149], v[178:181], v[126:129]
	v_mfma_f32_16x16x32_bf16 v[50:53], v[138:141], v[186:189], v[50:53]
	v_mfma_f32_16x16x32_bf16 v[62:65], v[146:149], v[186:189], v[62:65]
	v_mfma_f32_16x16x32_bf16 v[10:13], v[138:141], v[238:241], v[10:13]
	v_mfma_f32_16x16x32_bf16 v[14:17], v[146:149], v[238:241], v[14:17]
	v_mfma_f32_16x16x32_bf16 v[114:117], v[150:153], v[166:169], v[114:117]
	v_mfma_f32_16x16x32_bf16 v[122:125], v[158:161], v[166:169], v[122:125]
	v_mfma_f32_16x16x32_bf16 v[66:69], v[150:153], v[174:177], v[66:69]
	v_mfma_f32_16x16x32_bf16 v[78:81], v[158:161], v[174:177], v[78:81]
	v_mfma_f32_16x16x32_bf16 v[18:21], v[150:153], v[182:185], v[18:21]
	v_mfma_f32_16x16x32_bf16 v[22:25], v[158:161], v[182:185], v[22:25]
	v_mfma_f32_16x16x32_bf16 v[2:5], v[150:153], v[190:193], v[2:5]
	v_mfma_f32_16x16x32_bf16 v[6:9], v[158:161], v[190:193], v[6:9]
	v_mfma_f32_16x16x32_bf16 v[114:117], v[154:157], v[170:173], v[114:117]
	v_mfma_f32_16x16x32_bf16 v[122:125], v[162:165], v[170:173], v[122:125]
	v_mfma_f32_16x16x32_bf16 v[66:69], v[154:157], v[178:181], v[66:69]
	v_mfma_f32_16x16x32_bf16 v[78:81], v[162:165], v[178:181], v[78:81]
	v_mfma_f32_16x16x32_bf16 v[18:21], v[154:157], v[186:189], v[18:21]
	v_mfma_f32_16x16x32_bf16 v[22:25], v[162:165], v[186:189], v[22:25]
	v_mfma_f32_16x16x32_bf16 v[2:5], v[154:157], v[238:241], v[2:5]
	v_mfma_f32_16x16x32_bf16 v[6:9], v[162:165], v[238:241], v[6:9]
	s_barrier
	ds_read_b128 v[134:137], v235
	ds_read_b128 v[138:141], v235 offset:1024
	ds_read_b128 v[142:145], v235 offset:2048
	ds_read_b128 v[146:149], v235 offset:3072
	ds_read_b128 v[150:153], v236
	ds_read_b128 v[154:157], v236 offset:1024
	ds_read_b128 v[158:161], v236 offset:2048
	ds_read_b128 v[162:165], v236 offset:3072
	s_add_u32 s34, s34, 0x80000
	s_addc_u32 s35, s35, 0
	s_mov_b32 m0, s43
	v_lshl_add_u64 v[250:251], s[34:35], 0, v[194:195]
	ds_read_b128 v[166:169], v226 offset:32768
	ds_read_b128 v[170:173], v226 offset:33792
	ds_read_b128 v[174:177], v226 offset:34816
	ds_read_b128 v[178:181], v226 offset:35840
	ds_read_b128 v[182:185], v226 offset:36864
	ds_read_b128 v[186:189], v226 offset:37888
	ds_read_b128 v[190:193], v226 offset:38912
	ds_read_b128 v[238:241], v226 offset:39936
	global_load_lds_dwordx4 v[250:251], off
	v_lshl_add_u64 v[250:251], s[34:35], 0, v[204:205]
	s_mov_b32 m0, s44
	s_nop 0
	global_load_lds_dwordx4 v[250:251], off
	s_waitcnt vmcnt(8)
	s_waitcnt lgkmcnt(0)
	s_barrier
	s_waitcnt lgkmcnt(0)
	v_mfma_f32_16x16x32_bf16 v[26:29], v[134:137], v[166:169], v[26:29]
	v_mfma_f32_16x16x32_bf16 v[30:33], v[142:145], v[166:169], v[30:33]
	v_mfma_f32_16x16x32_bf16 v[42:45], v[134:137], v[174:177], v[42:45]
	v_mfma_f32_16x16x32_bf16 v[46:49], v[142:145], v[174:177], v[46:49]
	v_mfma_f32_16x16x32_bf16 v[70:73], v[134:137], v[182:185], v[70:73]
	v_mfma_f32_16x16x32_bf16 v[74:77], v[142:145], v[182:185], v[74:77]
	v_mfma_f32_16x16x32_bf16 v[90:93], v[134:137], v[190:193], v[90:93]
	v_mfma_f32_16x16x32_bf16 v[94:97], v[142:145], v[190:193], v[94:97]
	v_mfma_f32_16x16x32_bf16 v[26:29], v[138:141], v[170:173], v[26:29]
	v_mfma_f32_16x16x32_bf16 v[30:33], v[146:149], v[170:173], v[30:33]
	v_mfma_f32_16x16x32_bf16 v[42:45], v[138:141], v[178:181], v[42:45]
	v_mfma_f32_16x16x32_bf16 v[46:49], v[146:149], v[178:181], v[46:49]
	v_mfma_f32_16x16x32_bf16 v[70:73], v[138:141], v[186:189], v[70:73]
	v_mfma_f32_16x16x32_bf16 v[74:77], v[146:149], v[186:189], v[74:77]
	v_mfma_f32_16x16x32_bf16 v[90:93], v[138:141], v[238:241], v[90:93]
	v_mfma_f32_16x16x32_bf16 v[94:97], v[146:149], v[238:241], v[94:97]
	v_mfma_f32_16x16x32_bf16 v[34:37], v[150:153], v[166:169], v[34:37]
	v_mfma_f32_16x16x32_bf16 v[38:41], v[158:161], v[166:169], v[38:41]
	v_mfma_f32_16x16x32_bf16 v[54:57], v[150:153], v[174:177], v[54:57]
	v_mfma_f32_16x16x32_bf16 v[58:61], v[158:161], v[174:177], v[58:61]
	v_mfma_f32_16x16x32_bf16 v[82:85], v[150:153], v[182:185], v[82:85]
	v_mfma_f32_16x16x32_bf16 v[86:89], v[158:161], v[182:185], v[86:89]
	v_mfma_f32_16x16x32_bf16 v[98:101], v[150:153], v[190:193], v[98:101]
	v_mfma_f32_16x16x32_bf16 v[102:105], v[158:161], v[190:193], v[102:105]
	v_mfma_f32_16x16x32_bf16 v[34:37], v[154:157], v[170:173], v[34:37]
	v_mfma_f32_16x16x32_bf16 v[38:41], v[162:165], v[170:173], v[38:41]
	v_mfma_f32_16x16x32_bf16 v[54:57], v[154:157], v[178:181], v[54:57]
	v_mfma_f32_16x16x32_bf16 v[58:61], v[162:165], v[178:181], v[58:61]
	v_mfma_f32_16x16x32_bf16 v[82:85], v[154:157], v[186:189], v[82:85]
	v_mfma_f32_16x16x32_bf16 v[86:89], v[162:165], v[186:189], v[86:89]
	v_mfma_f32_16x16x32_bf16 v[98:101], v[154:157], v[238:241], v[98:101]
	v_mfma_f32_16x16x32_bf16 v[102:105], v[162:165], v[238:241], v[102:105]
	s_barrier
	s_mov_b32 m0, s72
	v_lshl_add_u64 v[242:243], v[242:243], 0, s[6:7]
	s_add_u32 s30, s30, 0x80080
	ds_read_b128 v[166:169], v226 offset:49152
	ds_read_b128 v[170:173], v226 offset:50176
	ds_read_b128 v[174:177], v226 offset:51200
	ds_read_b128 v[178:181], v226 offset:52224
	ds_read_b128 v[182:185], v226 offset:53248
	ds_read_b128 v[186:189], v226 offset:54272
	ds_read_b128 v[190:193], v226 offset:55296
	ds_read_b128 v[238:241], v226 offset:56320
	global_load_lds_dwordx4 v[242:243], off
	v_lshl_add_u64 v[242:243], v[244:245], 0, s[6:7]
	s_mov_b32 m0, s73
	s_addc_u32 s31, s31, 0
	global_load_lds_dwordx4 v[242:243], off
	v_lshl_add_u64 v[242:243], s[30:31], 0, v[202:203]
	s_mov_b32 m0, s74
	s_nop 0
	global_load_lds_dwordx4 v[242:243], off
	v_lshl_add_u64 v[242:243], s[30:31], 0, v[206:207]
	s_mov_b32 m0, s75
	s_nop 0
	global_load_lds_dwordx4 v[242:243], off
	v_lshl_add_u64 v[242:243], v[246:247], 0, s[6:7]
	s_mov_b32 m0, s51
	s_nop 0
	global_load_lds_dwordx4 v[242:243], off
	v_lshl_add_u64 v[242:243], v[248:249], 0, s[6:7]
	s_mov_b32 m0, s53
	s_nop 0
	global_load_lds_dwordx4 v[242:243], off
	s_waitcnt vmcnt(8)
	s_waitcnt lgkmcnt(0)
	s_barrier
	s_waitcnt lgkmcnt(0)
	v_mfma_f32_16x16x32_bf16 v[106:109], v[134:137], v[166:169], v[106:109]
	v_mfma_f32_16x16x32_bf16 v[110:113], v[142:145], v[166:169], v[110:113]
	v_mfma_f32_16x16x32_bf16 v[118:121], v[134:137], v[174:177], v[118:121]
	v_mfma_f32_16x16x32_bf16 v[126:129], v[142:145], v[174:177], v[126:129]
	v_mfma_f32_16x16x32_bf16 v[50:53], v[134:137], v[182:185], v[50:53]
	v_mfma_f32_16x16x32_bf16 v[62:65], v[142:145], v[182:185], v[62:65]
	v_mfma_f32_16x16x32_bf16 v[10:13], v[134:137], v[190:193], v[10:13]
	v_mfma_f32_16x16x32_bf16 v[14:17], v[142:145], v[190:193], v[14:17]
	v_mfma_f32_16x16x32_bf16 v[106:109], v[138:141], v[170:173], v[106:109]
	v_mfma_f32_16x16x32_bf16 v[110:113], v[146:149], v[170:173], v[110:113]
	v_mfma_f32_16x16x32_bf16 v[118:121], v[138:141], v[178:181], v[118:121]
	v_mfma_f32_16x16x32_bf16 v[126:129], v[146:149], v[178:181], v[126:129]
	v_mfma_f32_16x16x32_bf16 v[50:53], v[138:141], v[186:189], v[50:53]
	v_mfma_f32_16x16x32_bf16 v[62:65], v[146:149], v[186:189], v[62:65]
	v_mfma_f32_16x16x32_bf16 v[10:13], v[138:141], v[238:241], v[10:13]
	v_mfma_f32_16x16x32_bf16 v[14:17], v[146:149], v[238:241], v[14:17]
	v_mfma_f32_16x16x32_bf16 v[114:117], v[150:153], v[166:169], v[114:117]
	v_mfma_f32_16x16x32_bf16 v[122:125], v[158:161], v[166:169], v[122:125]
	v_mfma_f32_16x16x32_bf16 v[66:69], v[150:153], v[174:177], v[66:69]
	v_mfma_f32_16x16x32_bf16 v[78:81], v[158:161], v[174:177], v[78:81]
	v_mfma_f32_16x16x32_bf16 v[18:21], v[150:153], v[182:185], v[18:21]
	v_mfma_f32_16x16x32_bf16 v[22:25], v[158:161], v[182:185], v[22:25]
	v_mfma_f32_16x16x32_bf16 v[2:5], v[150:153], v[190:193], v[2:5]
	v_mfma_f32_16x16x32_bf16 v[6:9], v[158:161], v[190:193], v[6:9]
	v_mfma_f32_16x16x32_bf16 v[114:117], v[154:157], v[170:173], v[114:117]
	v_mfma_f32_16x16x32_bf16 v[122:125], v[162:165], v[170:173], v[122:125]
	v_mfma_f32_16x16x32_bf16 v[66:69], v[154:157], v[178:181], v[66:69]
	v_mfma_f32_16x16x32_bf16 v[78:81], v[162:165], v[178:181], v[78:81]
	v_mfma_f32_16x16x32_bf16 v[18:21], v[154:157], v[186:189], v[18:21]
	v_mfma_f32_16x16x32_bf16 v[22:25], v[162:165], v[186:189], v[22:25]
	v_mfma_f32_16x16x32_bf16 v[2:5], v[154:157], v[238:241], v[2:5]
	v_mfma_f32_16x16x32_bf16 v[6:9], v[162:165], v[238:241], v[6:9]
	s_add_i32 s41, s41, 2
	s_add_u32 s2, s2, 0x100
	s_addc_u32 s3, s3, 0
	s_cmp_gt_u32 s41, 29
	s_barrier
	s_cbranch_scc0 .LBB0_752
	s_and_b64 vcc, exec, s[8:9]
	s_cbranch_vccz .LBB0_755
	s_barrier

.LBB0_817:
	ds_read_b128 v[130:133], v223
	ds_read_b128 v[134:137], v223 offset:1024
	ds_read_b128 v[138:141], v223 offset:2048
	ds_read_b128 v[142:145], v223 offset:3072
	ds_read_b128 v[146:149], v224
	ds_read_b128 v[150:153], v224 offset:1024
	ds_read_b128 v[154:157], v224 offset:2048
	ds_read_b128 v[158:161], v224 offset:3072
	s_add_u32 s6, s4, 0xfff00080
	s_addc_u32 s7, s5, -1
	s_cmp_eq_u32 s14, 60
	s_cselect_b32 s9, s19, s7
	s_cselect_b32 s8, s18, s6
	s_cselect_b32 s7, s79, s1
	s_cselect_b32 s6, s78, s0
	v_lshl_add_u64 v[194:195], s[4:5], 0, v[170:171]
	s_add_i32 m0, s35, 0xc000
	ds_read_b128 v[174:177], v225
	ds_read_b128 v[178:181], v225 offset:1024
	ds_read_b128 v[182:185], v225 offset:2048
	ds_read_b128 v[186:189], v225 offset:3072
	ds_read_b128 v[190:193], v225 offset:4096
	ds_read_b128 v[202:205], v225 offset:5120
	ds_read_b128 v[206:209], v225 offset:6144
	ds_read_b128 v[210:213], v225 offset:7168
	global_load_lds_dwordx4 v[194:195], off
	v_lshl_add_u64 v[194:195], s[4:5], 0, v[172:173]
	s_add_i32 m0, s35, 0xe000
	s_nop 0
	global_load_lds_dwordx4 v[194:195], off
	s_waitcnt vmcnt(8)
	s_waitcnt lgkmcnt(0)
	s_barrier
	s_waitcnt lgkmcnt(0)
	v_mfma_f32_16x16x32_bf16 v[14:17], v[130:133], v[174:177], v[14:17]
	v_mfma_f32_16x16x32_bf16 v[10:13], v[138:141], v[174:177], v[10:13]
	v_mfma_f32_16x16x32_bf16 v[34:37], v[130:133], v[182:185], v[34:37]
	v_mfma_f32_16x16x32_bf16 v[26:29], v[138:141], v[182:185], v[26:29]
	v_mfma_f32_16x16x32_bf16 v[46:49], v[130:133], v[190:193], v[46:49]
	v_mfma_f32_16x16x32_bf16 v[42:45], v[138:141], v[190:193], v[42:45]
	v_mfma_f32_16x16x32_bf16 v[62:65], v[130:133], v[206:209], v[62:65]
	v_mfma_f32_16x16x32_bf16 v[58:61], v[138:141], v[206:209], v[58:61]
	v_mfma_f32_16x16x32_bf16 v[14:17], v[134:137], v[178:181], v[14:17]
	v_mfma_f32_16x16x32_bf16 v[10:13], v[142:145], v[178:181], v[10:13]
	v_mfma_f32_16x16x32_bf16 v[34:37], v[134:137], v[186:189], v[34:37]
	v_mfma_f32_16x16x32_bf16 v[26:29], v[142:145], v[186:189], v[26:29]
	v_mfma_f32_16x16x32_bf16 v[46:49], v[134:137], v[202:205], v[46:49]
	v_mfma_f32_16x16x32_bf16 v[42:45], v[142:145], v[202:205], v[42:45]
	v_mfma_f32_16x16x32_bf16 v[62:65], v[134:137], v[210:213], v[62:65]
	v_mfma_f32_16x16x32_bf16 v[58:61], v[142:145], v[210:213], v[58:61]
	v_mfma_f32_16x16x32_bf16 v[6:9], v[146:149], v[174:177], v[6:9]
	v_mfma_f32_16x16x32_bf16 v[2:5], v[154:157], v[174:177], v[2:5]
	v_mfma_f32_16x16x32_bf16 v[22:25], v[146:149], v[182:185], v[22:25]
	v_mfma_f32_16x16x32_bf16 v[18:21], v[154:157], v[182:185], v[18:21]
	v_mfma_f32_16x16x32_bf16 v[38:41], v[146:149], v[190:193], v[38:41]
	v_mfma_f32_16x16x32_bf16 v[30:33], v[154:157], v[190:193], v[30:33]
	v_mfma_f32_16x16x32_bf16 v[54:57], v[146:149], v[206:209], v[54:57]
	v_mfma_f32_16x16x32_bf16 v[50:53], v[154:157], v[206:209], v[50:53]
	v_mfma_f32_16x16x32_bf16 v[6:9], v[150:153], v[178:181], v[6:9]
	v_mfma_f32_16x16x32_bf16 v[2:5], v[158:161], v[178:181], v[2:5]
	v_mfma_f32_16x16x32_bf16 v[22:25], v[150:153], v[186:189], v[22:25]
	v_mfma_f32_16x16x32_bf16 v[18:21], v[158:161], v[186:189], v[18:21]
	v_mfma_f32_16x16x32_bf16 v[38:41], v[150:153], v[202:205], v[38:41]
	v_mfma_f32_16x16x32_bf16 v[30:33], v[158:161], v[202:205], v[30:33]
	v_mfma_f32_16x16x32_bf16 v[54:57], v[150:153], v[210:213], v[54:57]
	v_mfma_f32_16x16x32_bf16 v[50:53], v[158:161], v[210:213], v[50:53]
	s_barrier
	s_add_i32 s15, s17, s33
	v_lshl_add_u64 v[194:195], s[6:7], 0, v[164:165]
	s_mov_b32 m0, s15
	ds_read_b128 v[174:177], v225 offset:16384
	ds_read_b128 v[178:181], v225 offset:17408
	ds_read_b128 v[182:185], v225 offset:18432
	ds_read_b128 v[186:189], v225 offset:19456
	ds_read_b128 v[190:193], v225 offset:20480
	ds_read_b128 v[202:205], v225 offset:21504
	ds_read_b128 v[206:209], v225 offset:22528
	ds_read_b128 v[210:213], v225 offset:23552
	global_load_lds_dwordx4 v[194:195], off
	s_add_i32 m0, s15, 0x2000
	s_add_u32 s44, s6, 0x100000
	v_lshl_add_u64 v[214:215], s[6:7], 0, v[168:169]
	s_addc_u32 s45, s7, 0
	s_add_i32 s15, s55, s33
	global_load_lds_dwordx4 v[214:215], off
	v_lshl_add_u64 v[216:217], s[44:45], 0, v[164:165]
	s_mov_b32 m0, s15
	v_lshl_add_u64 v[218:219], s[8:9], 0, v[166:167]
	global_load_lds_dwordx4 v[216:217], off
	v_lshl_add_u64 v[216:217], s[44:45], 0, v[168:169]
	s_add_i32 m0, s15, 0x2000
	s_nop 0
	global_load_lds_dwordx4 v[216:217], off
	v_lshl_add_u64 v[216:217], s[8:9], 0, v[162:163]
	s_mov_b32 m0, s35
	s_nop 0
	global_load_lds_dwordx4 v[216:217], off
	s_mov_b32 m0, s80
	s_nop 0
	global_load_lds_dwordx4 v[218:219], off
	s_waitcnt vmcnt(8)
	s_waitcnt lgkmcnt(0)
	s_barrier
	s_waitcnt lgkmcnt(0)
	v_mfma_f32_16x16x32_bf16 v[78:81], v[130:133], v[174:177], v[78:81]
	v_mfma_f32_16x16x32_bf16 v[74:77], v[138:141], v[174:177], v[74:77]
	v_mfma_f32_16x16x32_bf16 v[94:97], v[130:133], v[182:185], v[94:97]
	v_mfma_f32_16x16x32_bf16 v[90:93], v[138:141], v[182:185], v[90:93]
	v_mfma_f32_16x16x32_bf16 v[110:113], v[130:133], v[190:193], v[110:113]
	v_mfma_f32_16x16x32_bf16 v[106:109], v[138:141], v[190:193], v[106:109]
	v_mfma_f32_16x16x32_bf16 v[118:121], v[130:133], v[206:209], v[118:121]
	v_mfma_f32_16x16x32_bf16 v[114:117], v[138:141], v[206:209], v[114:117]
	v_mfma_f32_16x16x32_bf16 v[78:81], v[134:137], v[178:181], v[78:81]
	v_mfma_f32_16x16x32_bf16 v[74:77], v[142:145], v[178:181], v[74:77]
	v_mfma_f32_16x16x32_bf16 v[94:97], v[134:137], v[186:189], v[94:97]
	v_mfma_f32_16x16x32_bf16 v[90:93], v[142:145], v[186:189], v[90:93]
	v_mfma_f32_16x16x32_bf16 v[110:113], v[134:137], v[202:205], v[110:113]
	v_mfma_f32_16x16x32_bf16 v[106:109], v[142:145], v[202:205], v[106:109]
	v_mfma_f32_16x16x32_bf16 v[118:121], v[134:137], v[210:213], v[118:121]
	v_mfma_f32_16x16x32_bf16 v[114:117], v[142:145], v[210:213], v[114:117]
	v_mfma_f32_16x16x32_bf16 v[70:73], v[146:149], v[174:177], v[70:73]
	v_mfma_f32_16x16x32_bf16 v[66:69], v[154:157], v[174:177], v[66:69]
	v_mfma_f32_16x16x32_bf16 v[86:89], v[146:149], v[182:185], v[86:89]
	v_mfma_f32_16x16x32_bf16 v[82:85], v[154:157], v[182:185], v[82:85]
	v_mfma_f32_16x16x32_bf16 v[102:105], v[146:149], v[190:193], v[102:105]
	v_mfma_f32_16x16x32_bf16 v[98:101], v[154:157], v[190:193], v[98:101]
	v_mfma_f32_16x16x32_bf16 v[122:125], v[146:149], v[206:209], v[122:125]
	v_mfma_f32_16x16x32_bf16 v[126:129], v[154:157], v[206:209], v[126:129]
	v_mfma_f32_16x16x32_bf16 v[70:73], v[150:153], v[178:181], v[70:73]
	v_mfma_f32_16x16x32_bf16 v[66:69], v[158:161], v[178:181], v[66:69]
	v_mfma_f32_16x16x32_bf16 v[86:89], v[150:153], v[186:189], v[86:89]
	v_mfma_f32_16x16x32_bf16 v[82:85], v[158:161], v[186:189], v[82:85]
	v_mfma_f32_16x16x32_bf16 v[102:105], v[150:153], v[202:205], v[102:105]
	v_mfma_f32_16x16x32_bf16 v[98:101], v[158:161], v[202:205], v[98:101]
	v_mfma_f32_16x16x32_bf16 v[122:125], v[150:153], v[210:213], v[122:125]
	v_mfma_f32_16x16x32_bf16 v[126:129], v[158:161], v[210:213], v[126:129]
	s_barrier
	s_add_i32 s56, 0, 0x18000
	s_add_i32 s57, 0, 0x1c000
	v_add_u32_e32 v142, s56, v222
	v_add_u32_e32 v158, s57, v222
	ds_read_b128 v[130:133], v142
	ds_read_b128 v[134:137], v142 offset:1024
	ds_read_b128 v[138:141], v142 offset:2048
	ds_read_b128 v[142:145], v142 offset:3072
	ds_read_b128 v[146:149], v158
	ds_read_b128 v[150:153], v158 offset:1024
	ds_read_b128 v[154:157], v158 offset:2048
	ds_read_b128 v[158:161], v158 offset:3072
	s_add_u32 s8, s8, 0x100000
	s_addc_u32 s9, s9, 0
	s_mov_b32 m0, s59
	v_lshl_add_u64 v[238:239], s[8:9], 0, v[162:163]
	ds_read_b128 v[174:177], v225 offset:32768
	ds_read_b128 v[178:181], v225 offset:33792
	ds_read_b128 v[182:185], v225 offset:34816
	ds_read_b128 v[186:189], v225 offset:35840
	ds_read_b128 v[190:193], v225 offset:36864
	ds_read_b128 v[202:205], v225 offset:37888
	ds_read_b128 v[206:209], v225 offset:38912
	ds_read_b128 v[210:213], v225 offset:39936
	global_load_lds_dwordx4 v[238:239], off
	v_lshl_add_u64 v[238:239], s[8:9], 0, v[166:167]
	s_mov_b32 m0, s60
	s_nop 0
	global_load_lds_dwordx4 v[238:239], off
	s_waitcnt vmcnt(8)
	s_waitcnt lgkmcnt(0)
	s_barrier
	s_waitcnt lgkmcnt(0)
	v_mfma_f32_16x16x32_bf16 v[14:17], v[130:133], v[174:177], v[14:17]
	v_mfma_f32_16x16x32_bf16 v[10:13], v[138:141], v[174:177], v[10:13]
	v_mfma_f32_16x16x32_bf16 v[34:37], v[130:133], v[182:185], v[34:37]
	v_mfma_f32_16x16x32_bf16 v[26:29], v[138:141], v[182:185], v[26:29]
	v_mfma_f32_16x16x32_bf16 v[46:49], v[130:133], v[190:193], v[46:49]
	v_mfma_f32_16x16x32_bf16 v[42:45], v[138:141], v[190:193], v[42:45]
	v_mfma_f32_16x16x32_bf16 v[62:65], v[130:133], v[206:209], v[62:65]
	v_mfma_f32_16x16x32_bf16 v[58:61], v[138:141], v[206:209], v[58:61]
	v_mfma_f32_16x16x32_bf16 v[14:17], v[134:137], v[178:181], v[14:17]
	v_mfma_f32_16x16x32_bf16 v[10:13], v[142:145], v[178:181], v[10:13]
	v_mfma_f32_16x16x32_bf16 v[34:37], v[134:137], v[186:189], v[34:37]
	v_mfma_f32_16x16x32_bf16 v[26:29], v[142:145], v[186:189], v[26:29]
	v_mfma_f32_16x16x32_bf16 v[46:49], v[134:137], v[202:205], v[46:49]
	v_mfma_f32_16x16x32_bf16 v[42:45], v[142:145], v[202:205], v[42:45]
	v_mfma_f32_16x16x32_bf16 v[62:65], v[134:137], v[210:213], v[62:65]
	v_mfma_f32_16x16x32_bf16 v[58:61], v[142:145], v[210:213], v[58:61]
	v_mfma_f32_16x16x32_bf16 v[6:9], v[146:149], v[174:177], v[6:9]
	v_mfma_f32_16x16x32_bf16 v[2:5], v[154:157], v[174:177], v[2:5]
	v_mfma_f32_16x16x32_bf16 v[22:25], v[146:149], v[182:185], v[22:25]
	v_mfma_f32_16x16x32_bf16 v[18:21], v[154:157], v[182:185], v[18:21]
	v_mfma_f32_16x16x32_bf16 v[38:41], v[146:149], v[190:193], v[38:41]
	v_mfma_f32_16x16x32_bf16 v[30:33], v[154:157], v[190:193], v[30:33]
	v_mfma_f32_16x16x32_bf16 v[54:57], v[146:149], v[206:209], v[54:57]
	v_mfma_f32_16x16x32_bf16 v[50:53], v[154:157], v[206:209], v[50:53]
	v_mfma_f32_16x16x32_bf16 v[6:9], v[150:153], v[178:181], v[6:9]
	v_mfma_f32_16x16x32_bf16 v[2:5], v[158:161], v[178:181], v[2:5]
	v_mfma_f32_16x16x32_bf16 v[22:25], v[150:153], v[186:189], v[22:25]
	v_mfma_f32_16x16x32_bf16 v[18:21], v[158:161], v[186:189], v[18:21]
	v_mfma_f32_16x16x32_bf16 v[38:41], v[150:153], v[202:205], v[38:41]
	v_mfma_f32_16x16x32_bf16 v[30:33], v[158:161], v[202:205], v[30:33]
	v_mfma_f32_16x16x32_bf16 v[54:57], v[150:153], v[210:213], v[54:57]
	v_mfma_f32_16x16x32_bf16 v[50:53], v[158:161], v[210:213], v[50:53]
	s_barrier
	s_add_i32 s8, s56, s33
	v_lshl_add_u64 v[194:195], v[194:195], 0, s[26:27]
	s_mov_b32 m0, s8
	ds_read_b128 v[174:177], v225 offset:49152
	ds_read_b128 v[178:181], v225 offset:50176
	ds_read_b128 v[182:185], v225 offset:51200
	ds_read_b128 v[186:189], v225 offset:52224
	ds_read_b128 v[190:193], v225 offset:53248
	ds_read_b128 v[202:205], v225 offset:54272
	ds_read_b128 v[206:209], v225 offset:55296
	ds_read_b128 v[210:213], v225 offset:56320
	global_load_lds_dwordx4 v[194:195], off
	s_add_i32 m0, s8, 0x2000
	s_add_u32 s6, s6, 0x100080
	v_lshl_add_u64 v[194:195], v[214:215], 0, s[26:27]
	s_addc_u32 s7, s7, 0
	s_add_i32 s8, s57, s33
	global_load_lds_dwordx4 v[194:195], off
	v_lshl_add_u64 v[194:195], s[6:7], 0, v[164:165]
	s_mov_b32 m0, s8
	s_nop 0
	global_load_lds_dwordx4 v[194:195], off
	v_lshl_add_u64 v[194:195], s[6:7], 0, v[168:169]
	s_add_i32 m0, s8, 0x2000
	s_nop 0
	global_load_lds_dwordx4 v[194:195], off
	v_lshl_add_u64 v[194:195], v[216:217], 0, s[26:27]
	s_mov_b32 m0, s65
	s_nop 0
	global_load_lds_dwordx4 v[194:195], off
	v_lshl_add_u64 v[194:195], v[218:219], 0, s[26:27]
	s_mov_b32 m0, s66
	s_nop 0
	global_load_lds_dwordx4 v[194:195], off
	s_waitcnt vmcnt(8)
	s_waitcnt lgkmcnt(0)
	s_barrier
	s_waitcnt lgkmcnt(0)
	v_mfma_f32_16x16x32_bf16 v[78:81], v[130:133], v[174:177], v[78:81]
	v_mfma_f32_16x16x32_bf16 v[74:77], v[138:141], v[174:177], v[74:77]
	v_mfma_f32_16x16x32_bf16 v[94:97], v[130:133], v[182:185], v[94:97]
	v_mfma_f32_16x16x32_bf16 v[90:93], v[138:141], v[182:185], v[90:93]
	v_mfma_f32_16x16x32_bf16 v[110:113], v[130:133], v[190:193], v[110:113]
	v_mfma_f32_16x16x32_bf16 v[106:109], v[138:141], v[190:193], v[106:109]
	v_mfma_f32_16x16x32_bf16 v[118:121], v[130:133], v[206:209], v[118:121]
	v_mfma_f32_16x16x32_bf16 v[114:117], v[138:141], v[206:209], v[114:117]
	v_mfma_f32_16x16x32_bf16 v[78:81], v[134:137], v[178:181], v[78:81]
	v_mfma_f32_16x16x32_bf16 v[74:77], v[142:145], v[178:181], v[74:77]
	v_mfma_f32_16x16x32_bf16 v[94:97], v[134:137], v[186:189], v[94:97]
	v_mfma_f32_16x16x32_bf16 v[90:93], v[142:145], v[186:189], v[90:93]
	v_mfma_f32_16x16x32_bf16 v[110:113], v[134:137], v[202:205], v[110:113]
	v_mfma_f32_16x16x32_bf16 v[106:109], v[142:145], v[202:205], v[106:109]
	v_mfma_f32_16x16x32_bf16 v[118:121], v[134:137], v[210:213], v[118:121]
	v_mfma_f32_16x16x32_bf16 v[114:117], v[142:145], v[210:213], v[114:117]
	v_mfma_f32_16x16x32_bf16 v[70:73], v[146:149], v[174:177], v[70:73]
	v_mfma_f32_16x16x32_bf16 v[66:69], v[154:157], v[174:177], v[66:69]
	v_mfma_f32_16x16x32_bf16 v[86:89], v[146:149], v[182:185], v[86:89]
	v_mfma_f32_16x16x32_bf16 v[82:85], v[154:157], v[182:185], v[82:85]
	v_mfma_f32_16x16x32_bf16 v[102:105], v[146:149], v[190:193], v[102:105]
	v_mfma_f32_16x16x32_bf16 v[98:101], v[154:157], v[190:193], v[98:101]
	v_mfma_f32_16x16x32_bf16 v[122:125], v[146:149], v[206:209], v[122:125]
	v_mfma_f32_16x16x32_bf16 v[126:129], v[154:157], v[206:209], v[126:129]
	v_mfma_f32_16x16x32_bf16 v[70:73], v[150:153], v[178:181], v[70:73]
	v_mfma_f32_16x16x32_bf16 v[66:69], v[158:161], v[178:181], v[66:69]
	v_mfma_f32_16x16x32_bf16 v[86:89], v[150:153], v[186:189], v[86:89]
	v_mfma_f32_16x16x32_bf16 v[82:85], v[158:161], v[186:189], v[82:85]
	v_mfma_f32_16x16x32_bf16 v[102:105], v[150:153], v[202:205], v[102:105]
	v_mfma_f32_16x16x32_bf16 v[98:101], v[158:161], v[202:205], v[98:101]
	v_mfma_f32_16x16x32_bf16 v[122:125], v[150:153], v[210:213], v[122:125]
	v_mfma_f32_16x16x32_bf16 v[126:129], v[158:161], v[210:213], v[126:129]
	s_add_i32 s14, s14, 2
	s_add_u32 s4, s4, 0x100
	s_addc_u32 s5, s5, 0
	s_add_u32 s0, s0, 0x100
	s_addc_u32 s1, s1, 0
	s_cmp_gt_u32 s14, 61
	s_barrier
	s_cbranch_scc0 .LBB0_817
	s_and_b64 vcc, exec, s[28:29]
	s_cbranch_vccz .LBB0_820
	s_barrier

.LBB0_961:
	ds_read_b128 v[158:161], v185
	ds_read_b128 v[154:157], v185 offset:1024
	ds_read_b128 v[150:153], v185 offset:2048
	ds_read_b128 v[146:149], v185 offset:3072
	ds_read_b128 v[142:145], v186
	ds_read_b128 v[138:141], v186 offset:1024
	ds_read_b128 v[134:137], v186 offset:2048
	ds_read_b128 v[130:133], v186 offset:3072
	s_add_u32 s30, s28, 0xfff80080
	s_addc_u32 s31, s29, -1
	s_cmp_eq_u32 s45, 28
	s_cselect_b32 s35, s1, s31
	s_cselect_b32 s34, s15, s30
	s_cselect_b32 s31, s19, s44
	s_cselect_b32 s30, s42, s43
	v_lshl_add_u64 v[220:221], s[28:29], 0, v[170:171]
	s_add_i32 m0, s27, 0xc000
	ds_read_b128 v[174:177], v187
	ds_read_b128 v[178:181], v187 offset:1024
	ds_read_b128 v[188:191], v187 offset:2048
	ds_read_b128 v[192:195], v187 offset:3072
	ds_read_b128 v[202:205], v187 offset:4096
	ds_read_b128 v[206:209], v187 offset:5120
	ds_read_b128 v[210:213], v187 offset:6144
	ds_read_b128 v[214:217], v187 offset:7168
	global_load_lds_dwordx4 v[220:221], off
	v_lshl_add_u64 v[220:221], s[28:29], 0, v[172:173]
	s_add_i32 m0, s27, 0xe000
	s_nop 0
	global_load_lds_dwordx4 v[220:221], off
	s_waitcnt vmcnt(8)
	s_waitcnt lgkmcnt(0)
	s_barrier
	s_waitcnt lgkmcnt(0)
	v_mfma_i32_16x16x64_i8 v[126:129], v[158:161], v[174:177], v[126:129]
	v_mfma_i32_16x16x64_i8 v[126:129], v[154:157], v[178:181], v[126:129]
	v_mfma_i32_16x16x64_i8 v[122:125], v[150:153], v[174:177], v[122:125]
	v_mfma_i32_16x16x64_i8 v[122:125], v[146:149], v[178:181], v[122:125]
	v_mfma_i32_16x16x64_i8 v[110:113], v[158:161], v[188:191], v[110:113]
	v_mfma_i32_16x16x64_i8 v[110:113], v[154:157], v[192:195], v[110:113]
	v_mfma_i32_16x16x64_i8 v[106:109], v[150:153], v[188:191], v[106:109]
	v_mfma_i32_16x16x64_i8 v[106:109], v[146:149], v[192:195], v[106:109]
	v_mfma_i32_16x16x64_i8 v[94:97], v[158:161], v[202:205], v[94:97]
	v_mfma_i32_16x16x64_i8 v[94:97], v[154:157], v[206:209], v[94:97]
	v_mfma_i32_16x16x64_i8 v[90:93], v[150:153], v[202:205], v[90:93]
	v_mfma_i32_16x16x64_i8 v[90:93], v[146:149], v[206:209], v[90:93]
	v_mfma_i32_16x16x64_i8 v[78:81], v[158:161], v[210:213], v[78:81]
	v_mfma_i32_16x16x64_i8 v[78:81], v[154:157], v[214:217], v[78:81]
	v_mfma_i32_16x16x64_i8 v[74:77], v[150:153], v[210:213], v[74:77]
	v_mfma_i32_16x16x64_i8 v[74:77], v[146:149], v[214:217], v[74:77]
	v_mfma_i32_16x16x64_i8 v[118:121], v[142:145], v[174:177], v[118:121]
	v_mfma_i32_16x16x64_i8 v[118:121], v[138:141], v[178:181], v[118:121]
	v_mfma_i32_16x16x64_i8 v[114:117], v[134:137], v[174:177], v[114:117]
	v_mfma_i32_16x16x64_i8 v[114:117], v[130:133], v[178:181], v[114:117]
	v_mfma_i32_16x16x64_i8 v[102:105], v[142:145], v[188:191], v[102:105]
	v_mfma_i32_16x16x64_i8 v[102:105], v[138:141], v[192:195], v[102:105]
	v_mfma_i32_16x16x64_i8 v[98:101], v[134:137], v[188:191], v[98:101]
	v_mfma_i32_16x16x64_i8 v[98:101], v[130:133], v[192:195], v[98:101]
	v_mfma_i32_16x16x64_i8 v[86:89], v[142:145], v[202:205], v[86:89]
	v_mfma_i32_16x16x64_i8 v[86:89], v[138:141], v[206:209], v[86:89]
	v_mfma_i32_16x16x64_i8 v[82:85], v[134:137], v[202:205], v[82:85]
	v_mfma_i32_16x16x64_i8 v[82:85], v[130:133], v[206:209], v[82:85]
	v_mfma_i32_16x16x64_i8 v[70:73], v[142:145], v[210:213], v[70:73]
	v_mfma_i32_16x16x64_i8 v[70:73], v[138:141], v[214:217], v[70:73]
	v_mfma_i32_16x16x64_i8 v[66:69], v[134:137], v[210:213], v[66:69]
	v_mfma_i32_16x16x64_i8 v[66:69], v[130:133], v[214:217], v[66:69]
	s_barrier
	s_add_i32 s46, s17, s9
	v_lshl_add_u64 v[174:175], s[30:31], 0, v[166:167]
	s_mov_b32 m0, s46
	ds_read_b128 v[188:191], v187 offset:16384
	ds_read_b128 v[192:195], v187 offset:17408
	ds_read_b128 v[202:205], v187 offset:18432
	ds_read_b128 v[206:209], v187 offset:19456
	ds_read_b128 v[210:213], v187 offset:20480
	ds_read_b128 v[214:217], v187 offset:21504
	ds_read_b128 v[220:223], v187 offset:22528
	ds_read_b128 v[224:227], v187 offset:23552
	global_load_lds_dwordx4 v[174:175], off
	s_add_i32 m0, s46, 0x2000
	s_add_u32 s46, s30, 0x80000
	v_lshl_add_u64 v[176:177], s[30:31], 0, v[162:163]
	s_addc_u32 s47, s31, 0
	s_add_i32 s48, s55, s9
	global_load_lds_dwordx4 v[176:177], off
	v_lshl_add_u64 v[178:179], s[46:47], 0, v[166:167]
	s_mov_b32 m0, s48
	v_lshl_add_u64 v[180:181], s[34:35], 0, v[164:165]
	global_load_lds_dwordx4 v[178:179], off
	v_lshl_add_u64 v[178:179], s[46:47], 0, v[162:163]
	s_add_i32 m0, s48, 0x2000
	s_nop 0
	global_load_lds_dwordx4 v[178:179], off
	v_lshl_add_u64 v[178:179], s[34:35], 0, v[168:169]
	s_mov_b32 m0, s27
	s_nop 0
	global_load_lds_dwordx4 v[178:179], off
	s_mov_b32 m0, s33
	s_nop 0
	global_load_lds_dwordx4 v[180:181], off
	s_waitcnt vmcnt(8)
	s_waitcnt lgkmcnt(0)
	s_barrier
	s_waitcnt lgkmcnt(0)
	v_mfma_i32_16x16x64_i8 v[62:65], v[158:161], v[188:191], v[62:65]
	v_mfma_i32_16x16x64_i8 v[62:65], v[154:157], v[192:195], v[62:65]
	v_mfma_i32_16x16x64_i8 v[58:61], v[150:153], v[188:191], v[58:61]
	v_mfma_i32_16x16x64_i8 v[58:61], v[146:149], v[192:195], v[58:61]
	v_mfma_i32_16x16x64_i8 v[46:49], v[158:161], v[202:205], v[46:49]
	v_mfma_i32_16x16x64_i8 v[46:49], v[154:157], v[206:209], v[46:49]
	v_mfma_i32_16x16x64_i8 v[42:45], v[150:153], v[202:205], v[42:45]
	v_mfma_i32_16x16x64_i8 v[42:45], v[146:149], v[206:209], v[42:45]
	v_mfma_i32_16x16x64_i8 v[30:33], v[158:161], v[210:213], v[30:33]
	v_mfma_i32_16x16x64_i8 v[30:33], v[154:157], v[214:217], v[30:33]
	v_mfma_i32_16x16x64_i8 v[26:29], v[150:153], v[210:213], v[26:29]
	v_mfma_i32_16x16x64_i8 v[26:29], v[146:149], v[214:217], v[26:29]
	v_mfma_i32_16x16x64_i8 v[14:17], v[158:161], v[220:223], v[14:17]
	v_mfma_i32_16x16x64_i8 v[14:17], v[154:157], v[224:227], v[14:17]
	v_mfma_i32_16x16x64_i8 v[10:13], v[150:153], v[220:223], v[10:13]
	v_mfma_i32_16x16x64_i8 v[10:13], v[146:149], v[224:227], v[10:13]
	v_mfma_i32_16x16x64_i8 v[54:57], v[142:145], v[188:191], v[54:57]
	v_mfma_i32_16x16x64_i8 v[54:57], v[138:141], v[192:195], v[54:57]
	v_mfma_i32_16x16x64_i8 v[50:53], v[134:137], v[188:191], v[50:53]
	v_mfma_i32_16x16x64_i8 v[50:53], v[130:133], v[192:195], v[50:53]
	v_mfma_i32_16x16x64_i8 v[38:41], v[142:145], v[202:205], v[38:41]
	v_mfma_i32_16x16x64_i8 v[38:41], v[138:141], v[206:209], v[38:41]
	v_mfma_i32_16x16x64_i8 v[34:37], v[134:137], v[202:205], v[34:37]
	v_mfma_i32_16x16x64_i8 v[34:37], v[130:133], v[206:209], v[34:37]
	v_mfma_i32_16x16x64_i8 v[22:25], v[142:145], v[210:213], v[22:25]
	v_mfma_i32_16x16x64_i8 v[22:25], v[138:141], v[214:217], v[22:25]
	v_mfma_i32_16x16x64_i8 v[18:21], v[134:137], v[210:213], v[18:21]
	v_mfma_i32_16x16x64_i8 v[18:21], v[130:133], v[214:217], v[18:21]
	v_mfma_i32_16x16x64_i8 v[6:9], v[142:145], v[220:223], v[6:9]
	v_mfma_i32_16x16x64_i8 v[6:9], v[138:141], v[224:227], v[6:9]
	v_mfma_i32_16x16x64_i8 v[2:5], v[134:137], v[220:223], v[2:5]
	v_mfma_i32_16x16x64_i8 v[2:5], v[130:133], v[224:227], v[2:5]
	s_barrier
	v_add_u32_e32 v142, s56, v183
	v_add_u32_e32 v158, s57, v183
	ds_read_b128 v[130:133], v142
	ds_read_b128 v[134:137], v142 offset:1024
	ds_read_b128 v[138:141], v142 offset:2048
	ds_read_b128 v[142:145], v142 offset:3072
	ds_read_b128 v[146:149], v158
	ds_read_b128 v[150:153], v158 offset:1024
	ds_read_b128 v[154:157], v158 offset:2048
	ds_read_b128 v[158:161], v158 offset:3072
	s_add_u32 s34, s34, 0x80000
	s_addc_u32 s35, s35, 0
	s_mov_b32 m0, s36
	v_lshl_add_u64 v[232:233], s[34:35], 0, v[168:169]
	ds_read_b128 v[188:191], v187 offset:32768
	ds_read_b128 v[192:195], v187 offset:33792
	ds_read_b128 v[202:205], v187 offset:34816
	ds_read_b128 v[206:209], v187 offset:35840
	ds_read_b128 v[210:213], v187 offset:36864
	ds_read_b128 v[214:217], v187 offset:37888
	ds_read_b128 v[220:223], v187 offset:38912
	ds_read_b128 v[224:227], v187 offset:39936
	global_load_lds_dwordx4 v[232:233], off
	v_lshl_add_u64 v[232:233], s[34:35], 0, v[164:165]
	s_mov_b32 m0, s37
	s_nop 0
	global_load_lds_dwordx4 v[232:233], off
	s_waitcnt vmcnt(8)
	s_waitcnt lgkmcnt(0)
	s_barrier
	s_waitcnt lgkmcnt(0)
	v_mfma_i32_16x16x64_i8 v[126:129], v[130:133], v[188:191], v[126:129]
	v_mfma_i32_16x16x64_i8 v[126:129], v[134:137], v[192:195], v[126:129]
	v_mfma_i32_16x16x64_i8 v[122:125], v[138:141], v[188:191], v[122:125]
	v_mfma_i32_16x16x64_i8 v[122:125], v[142:145], v[192:195], v[122:125]
	v_mfma_i32_16x16x64_i8 v[110:113], v[130:133], v[202:205], v[110:113]
	v_mfma_i32_16x16x64_i8 v[110:113], v[134:137], v[206:209], v[110:113]
	v_mfma_i32_16x16x64_i8 v[106:109], v[138:141], v[202:205], v[106:109]
	v_mfma_i32_16x16x64_i8 v[106:109], v[142:145], v[206:209], v[106:109]
	v_mfma_i32_16x16x64_i8 v[94:97], v[130:133], v[210:213], v[94:97]
	v_mfma_i32_16x16x64_i8 v[94:97], v[134:137], v[214:217], v[94:97]
	v_mfma_i32_16x16x64_i8 v[90:93], v[138:141], v[210:213], v[90:93]
	v_mfma_i32_16x16x64_i8 v[90:93], v[142:145], v[214:217], v[90:93]
	v_mfma_i32_16x16x64_i8 v[78:81], v[130:133], v[220:223], v[78:81]
	v_mfma_i32_16x16x64_i8 v[78:81], v[134:137], v[224:227], v[78:81]
	v_mfma_i32_16x16x64_i8 v[74:77], v[138:141], v[220:223], v[74:77]
	v_mfma_i32_16x16x64_i8 v[74:77], v[142:145], v[224:227], v[74:77]
	v_mfma_i32_16x16x64_i8 v[118:121], v[146:149], v[188:191], v[118:121]
	v_mfma_i32_16x16x64_i8 v[118:121], v[150:153], v[192:195], v[118:121]
	v_mfma_i32_16x16x64_i8 v[114:117], v[154:157], v[188:191], v[114:117]
	v_mfma_i32_16x16x64_i8 v[114:117], v[158:161], v[192:195], v[114:117]
	v_mfma_i32_16x16x64_i8 v[102:105], v[146:149], v[202:205], v[102:105]
	v_mfma_i32_16x16x64_i8 v[102:105], v[150:153], v[206:209], v[102:105]
	v_mfma_i32_16x16x64_i8 v[98:101], v[154:157], v[202:205], v[98:101]
	v_mfma_i32_16x16x64_i8 v[98:101], v[158:161], v[206:209], v[98:101]
	v_mfma_i32_16x16x64_i8 v[86:89], v[146:149], v[210:213], v[86:89]
	v_mfma_i32_16x16x64_i8 v[86:89], v[150:153], v[214:217], v[86:89]
	v_mfma_i32_16x16x64_i8 v[82:85], v[154:157], v[210:213], v[82:85]
	v_mfma_i32_16x16x64_i8 v[82:85], v[158:161], v[214:217], v[82:85]
	v_mfma_i32_16x16x64_i8 v[70:73], v[146:149], v[220:223], v[70:73]
	v_mfma_i32_16x16x64_i8 v[70:73], v[150:153], v[224:227], v[70:73]
	v_mfma_i32_16x16x64_i8 v[66:69], v[154:157], v[220:223], v[66:69]
	v_mfma_i32_16x16x64_i8 v[66:69], v[158:161], v[224:227], v[66:69]
	s_barrier
	s_add_i32 s34, s56, s9
	v_lshl_add_u64 v[174:175], v[174:175], 0, s[4:5]
	s_mov_b32 m0, s34
	ds_read_b128 v[188:191], v187 offset:49152
	ds_read_b128 v[192:195], v187 offset:50176
	ds_read_b128 v[202:205], v187 offset:51200
	ds_read_b128 v[206:209], v187 offset:52224
	ds_read_b128 v[210:213], v187 offset:53248
	ds_read_b128 v[214:217], v187 offset:54272
	ds_read_b128 v[220:223], v187 offset:55296
	ds_read_b128 v[224:227], v187 offset:56320
	global_load_lds_dwordx4 v[174:175], off
	s_add_i32 m0, s34, 0x2000
	s_add_u32 s30, s30, 0x80080
	v_lshl_add_u64 v[174:175], v[176:177], 0, s[4:5]
	s_addc_u32 s31, s31, 0
	s_add_i32 s34, s57, s9
	global_load_lds_dwordx4 v[174:175], off
	v_lshl_add_u64 v[174:175], s[30:31], 0, v[166:167]
	s_mov_b32 m0, s34
	s_nop 0
	global_load_lds_dwordx4 v[174:175], off
	v_lshl_add_u64 v[174:175], s[30:31], 0, v[162:163]
	s_add_i32 m0, s34, 0x2000
	s_nop 0
	global_load_lds_dwordx4 v[174:175], off
	v_lshl_add_u64 v[174:175], v[178:179], 0, s[4:5]
	s_mov_b32 m0, s39
	s_nop 0
	global_load_lds_dwordx4 v[174:175], off
	v_lshl_add_u64 v[174:175], v[180:181], 0, s[4:5]
	s_mov_b32 m0, s40
	s_nop 0
	global_load_lds_dwordx4 v[174:175], off
	s_waitcnt vmcnt(8)
	s_waitcnt lgkmcnt(0)
	s_barrier
	s_waitcnt lgkmcnt(0)
	v_mfma_i32_16x16x64_i8 v[62:65], v[130:133], v[188:191], v[62:65]
	v_mfma_i32_16x16x64_i8 v[62:65], v[134:137], v[192:195], v[62:65]
	v_mfma_i32_16x16x64_i8 v[58:61], v[138:141], v[188:191], v[58:61]
	v_mfma_i32_16x16x64_i8 v[58:61], v[142:145], v[192:195], v[58:61]
	v_mfma_i32_16x16x64_i8 v[46:49], v[130:133], v[202:205], v[46:49]
	v_mfma_i32_16x16x64_i8 v[46:49], v[134:137], v[206:209], v[46:49]
	v_mfma_i32_16x16x64_i8 v[42:45], v[138:141], v[202:205], v[42:45]
	v_mfma_i32_16x16x64_i8 v[42:45], v[142:145], v[206:209], v[42:45]
	v_mfma_i32_16x16x64_i8 v[30:33], v[130:133], v[210:213], v[30:33]
	v_mfma_i32_16x16x64_i8 v[30:33], v[134:137], v[214:217], v[30:33]
	v_mfma_i32_16x16x64_i8 v[26:29], v[138:141], v[210:213], v[26:29]
	v_mfma_i32_16x16x64_i8 v[26:29], v[142:145], v[214:217], v[26:29]
	v_mfma_i32_16x16x64_i8 v[14:17], v[130:133], v[220:223], v[14:17]
	v_mfma_i32_16x16x64_i8 v[14:17], v[134:137], v[224:227], v[14:17]
	v_mfma_i32_16x16x64_i8 v[10:13], v[138:141], v[220:223], v[10:13]
	v_mfma_i32_16x16x64_i8 v[10:13], v[142:145], v[224:227], v[10:13]
	v_mfma_i32_16x16x64_i8 v[54:57], v[146:149], v[188:191], v[54:57]
	v_mfma_i32_16x16x64_i8 v[54:57], v[150:153], v[192:195], v[54:57]
	v_mfma_i32_16x16x64_i8 v[50:53], v[154:157], v[188:191], v[50:53]
	v_mfma_i32_16x16x64_i8 v[50:53], v[158:161], v[192:195], v[50:53]
	v_mfma_i32_16x16x64_i8 v[38:41], v[146:149], v[202:205], v[38:41]
	v_mfma_i32_16x16x64_i8 v[38:41], v[150:153], v[206:209], v[38:41]
	v_mfma_i32_16x16x64_i8 v[34:37], v[154:157], v[202:205], v[34:37]
	v_mfma_i32_16x16x64_i8 v[34:37], v[158:161], v[206:209], v[34:37]
	v_mfma_i32_16x16x64_i8 v[22:25], v[146:149], v[210:213], v[22:25]
	v_mfma_i32_16x16x64_i8 v[22:25], v[150:153], v[214:217], v[22:25]
	v_mfma_i32_16x16x64_i8 v[18:21], v[154:157], v[210:213], v[18:21]
	v_mfma_i32_16x16x64_i8 v[18:21], v[158:161], v[214:217], v[18:21]
	v_mfma_i32_16x16x64_i8 v[6:9], v[146:149], v[220:223], v[6:9]
	v_mfma_i32_16x16x64_i8 v[6:9], v[150:153], v[224:227], v[6:9]
	v_mfma_i32_16x16x64_i8 v[2:5], v[154:157], v[220:223], v[2:5]
	v_mfma_i32_16x16x64_i8 v[2:5], v[158:161], v[224:227], v[2:5]
	s_add_i32 s45, s45, 2
	s_add_u32 s28, s28, 0x100
	s_addc_u32 s29, s29, 0
	s_add_u32 s43, s43, 0x100
	s_addc_u32 s44, s44, 0
	s_cmp_gt_u32 s45, 29
	s_barrier
	s_cbranch_scc0 .LBB0_961
	s_nop 15
	s_nop 15
	s_and_b64 vcc, exec, s[6:7]
	s_cbranch_vccz .LBB0_964
	s_barrier

.LBB0_1058:
	ds_read_b128 v[128:131], v194
	ds_read_b128 v[132:135], v194 offset:1024
	ds_read_b128 v[136:139], v194 offset:2048
	ds_read_b128 v[140:143], v194 offset:3072
	ds_read_b128 v[144:147], v195
	ds_read_b128 v[148:151], v195 offset:1024
	ds_read_b128 v[152:155], v195 offset:2048
	ds_read_b128 v[156:159], v195 offset:3072
	s_add_u32 s2, s0, 0x100
	s_addc_u32 s3, s1, 0
	s_cmpk_eq_i32 s39, 0xa8
	s_cselect_b32 s37, s31, s3
	s_cselect_b32 s36, s30, s2
	s_cselect_b32 s5, s7, s38
	s_cselect_b32 s4, s6, s29
	v_lshl_add_u64 v[188:189], s[0:1], 0, v[168:169]
	s_add_i32 m0, s27, 0xc000
	ds_read_b128 v[172:175], v196
	ds_read_b128 v[176:179], v196 offset:1024
	ds_read_b128 v[180:183], v196 offset:2048
	ds_read_b128 v[184:187], v196 offset:3072
	ds_read_b128 v[200:203], v196 offset:4096
	ds_read_b128 v[204:207], v196 offset:5120
	ds_read_b128 v[208:211], v196 offset:6144
	ds_read_b128 v[212:215], v196 offset:7168
	global_load_lds_dwordx4 v[188:189], off
	v_lshl_add_u64 v[188:189], s[0:1], 0, v[170:171]
	s_add_i32 m0, s27, 0xe000
	s_nop 0
	global_load_lds_dwordx4 v[188:189], off
	s_waitcnt vmcnt(8)
	s_waitcnt lgkmcnt(0)
	s_barrier
	s_waitcnt lgkmcnt(0)
	v_mfma_f32_16x16x32_bf16 v[12:15], v[128:131], v[172:175], v[12:15]
	v_mfma_f32_16x16x32_bf16 v[8:11], v[136:139], v[172:175], v[8:11]
	v_mfma_f32_16x16x32_bf16 v[36:39], v[128:131], v[180:183], v[36:39]
	v_mfma_f32_16x16x32_bf16 v[32:35], v[136:139], v[180:183], v[32:35]
	v_mfma_f32_16x16x32_bf16 v[44:47], v[128:131], v[200:203], v[44:47]
	v_mfma_f32_16x16x32_bf16 v[40:43], v[136:139], v[200:203], v[40:43]
	v_mfma_f32_16x16x32_bf16 v[64:67], v[128:131], v[208:211], v[64:67]
	v_mfma_f32_16x16x32_bf16 v[56:59], v[136:139], v[208:211], v[56:59]
	v_mfma_f32_16x16x32_bf16 v[12:15], v[132:135], v[176:179], v[12:15]
	v_mfma_f32_16x16x32_bf16 v[8:11], v[140:143], v[176:179], v[8:11]
	v_mfma_f32_16x16x32_bf16 v[36:39], v[132:135], v[184:187], v[36:39]
	v_mfma_f32_16x16x32_bf16 v[32:35], v[140:143], v[184:187], v[32:35]
	v_mfma_f32_16x16x32_bf16 v[44:47], v[132:135], v[204:207], v[44:47]
	v_mfma_f32_16x16x32_bf16 v[40:43], v[140:143], v[204:207], v[40:43]
	v_mfma_f32_16x16x32_bf16 v[64:67], v[132:135], v[212:215], v[64:67]
	v_mfma_f32_16x16x32_bf16 v[56:59], v[140:143], v[212:215], v[56:59]
	v_mfma_f32_16x16x32_bf16 v[4:7], v[144:147], v[172:175], v[4:7]
	v_mfma_f32_16x16x32_bf16 v[0:3], v[152:155], v[172:175], v[0:3]
	v_mfma_f32_16x16x32_bf16 v[24:27], v[144:147], v[180:183], v[24:27]
	v_mfma_f32_16x16x32_bf16 v[16:19], v[152:155], v[180:183], v[16:19]
	v_mfma_f32_16x16x32_bf16 v[28:31], v[144:147], v[200:203], v[28:31]
	v_mfma_f32_16x16x32_bf16 v[20:23], v[152:155], v[200:203], v[20:23]
	v_mfma_f32_16x16x32_bf16 v[52:55], v[144:147], v[208:211], v[52:55]
	v_mfma_f32_16x16x32_bf16 v[48:51], v[152:155], v[208:211], v[48:51]
	v_mfma_f32_16x16x32_bf16 v[4:7], v[148:151], v[176:179], v[4:7]
	v_mfma_f32_16x16x32_bf16 v[0:3], v[156:159], v[176:179], v[0:3]
	v_mfma_f32_16x16x32_bf16 v[24:27], v[148:151], v[184:187], v[24:27]
	v_mfma_f32_16x16x32_bf16 v[16:19], v[156:159], v[184:187], v[16:19]
	v_mfma_f32_16x16x32_bf16 v[28:31], v[148:151], v[204:207], v[28:31]
	v_mfma_f32_16x16x32_bf16 v[20:23], v[156:159], v[204:207], v[20:23]
	v_mfma_f32_16x16x32_bf16 v[52:55], v[148:151], v[212:215], v[52:55]
	v_mfma_f32_16x16x32_bf16 v[48:51], v[156:159], v[212:215], v[48:51]
	s_barrier
	s_add_i32 s0, s17, s25
	v_lshl_add_u64 v[188:189], s[4:5], 0, v[162:163]
	s_mov_b32 m0, s0
	ds_read_b128 v[172:175], v196 offset:16384
	ds_read_b128 v[176:179], v196 offset:17408
	ds_read_b128 v[180:183], v196 offset:18432
	ds_read_b128 v[184:187], v196 offset:19456
	ds_read_b128 v[200:203], v196 offset:20480
	ds_read_b128 v[204:207], v196 offset:21504
	ds_read_b128 v[208:211], v196 offset:22528
	ds_read_b128 v[212:215], v196 offset:23552
	global_load_lds_dwordx4 v[188:189], off
	s_add_i32 m0, s0, 0x2000
	s_add_u32 s0, s4, 0x2b0000
	v_lshl_add_u64 v[216:217], s[4:5], 0, v[166:167]
	s_addc_u32 s1, s5, 0
	s_add_i32 s40, s55, s25
	global_load_lds_dwordx4 v[216:217], off
	v_lshl_add_u64 v[220:221], s[0:1], 0, v[162:163]
	s_mov_b32 m0, s40
	v_lshl_add_u64 v[222:223], s[36:37], 0, v[164:165]
	global_load_lds_dwordx4 v[220:221], off
	v_lshl_add_u64 v[220:221], s[0:1], 0, v[166:167]
	s_add_i32 m0, s40, 0x2000
	s_nop 0
	global_load_lds_dwordx4 v[220:221], off
	v_lshl_add_u64 v[220:221], s[36:37], 0, v[160:161]
	s_mov_b32 m0, s27
	s_nop 0
	global_load_lds_dwordx4 v[220:221], off
	s_mov_b32 m0, s33
	s_nop 0
	global_load_lds_dwordx4 v[222:223], off
	s_waitcnt vmcnt(8)
	s_waitcnt lgkmcnt(0)
	s_barrier
	s_waitcnt lgkmcnt(0)
	v_mfma_f32_16x16x32_bf16 v[76:79], v[128:131], v[172:175], v[76:79]
	v_mfma_f32_16x16x32_bf16 v[72:75], v[136:139], v[172:175], v[72:75]
	v_mfma_f32_16x16x32_bf16 v[92:95], v[128:131], v[180:183], v[92:95]
	v_mfma_f32_16x16x32_bf16 v[88:91], v[136:139], v[180:183], v[88:91]
	v_mfma_f32_16x16x32_bf16 v[108:111], v[128:131], v[200:203], v[108:111]
	v_mfma_f32_16x16x32_bf16 v[104:107], v[136:139], v[200:203], v[104:107]
	v_mfma_f32_16x16x32_bf16 v[124:127], v[128:131], v[208:211], v[124:127]
	v_mfma_f32_16x16x32_bf16 v[120:123], v[136:139], v[208:211], v[120:123]
	v_mfma_f32_16x16x32_bf16 v[76:79], v[132:135], v[176:179], v[76:79]
	v_mfma_f32_16x16x32_bf16 v[72:75], v[140:143], v[176:179], v[72:75]
	v_mfma_f32_16x16x32_bf16 v[92:95], v[132:135], v[184:187], v[92:95]
	v_mfma_f32_16x16x32_bf16 v[88:91], v[140:143], v[184:187], v[88:91]
	v_mfma_f32_16x16x32_bf16 v[108:111], v[132:135], v[204:207], v[108:111]
	v_mfma_f32_16x16x32_bf16 v[104:107], v[140:143], v[204:207], v[104:107]
	v_mfma_f32_16x16x32_bf16 v[124:127], v[132:135], v[212:215], v[124:127]
	v_mfma_f32_16x16x32_bf16 v[120:123], v[140:143], v[212:215], v[120:123]
	v_mfma_f32_16x16x32_bf16 v[68:71], v[144:147], v[172:175], v[68:71]
	v_mfma_f32_16x16x32_bf16 v[60:63], v[152:155], v[172:175], v[60:63]
	v_mfma_f32_16x16x32_bf16 v[84:87], v[144:147], v[180:183], v[84:87]
	v_mfma_f32_16x16x32_bf16 v[80:83], v[152:155], v[180:183], v[80:83]
	v_mfma_f32_16x16x32_bf16 v[100:103], v[144:147], v[200:203], v[100:103]
	v_mfma_f32_16x16x32_bf16 v[96:99], v[152:155], v[200:203], v[96:99]
	v_mfma_f32_16x16x32_bf16 v[116:119], v[144:147], v[208:211], v[116:119]
	v_mfma_f32_16x16x32_bf16 v[112:115], v[152:155], v[208:211], v[112:115]
	v_mfma_f32_16x16x32_bf16 v[68:71], v[148:151], v[176:179], v[68:71]
	v_mfma_f32_16x16x32_bf16 v[60:63], v[156:159], v[176:179], v[60:63]
	v_mfma_f32_16x16x32_bf16 v[84:87], v[148:151], v[184:187], v[84:87]
	v_mfma_f32_16x16x32_bf16 v[80:83], v[156:159], v[184:187], v[80:83]
	v_mfma_f32_16x16x32_bf16 v[100:103], v[148:151], v[204:207], v[100:103]
	v_mfma_f32_16x16x32_bf16 v[96:99], v[156:159], v[204:207], v[96:99]
	v_mfma_f32_16x16x32_bf16 v[116:119], v[148:151], v[212:215], v[116:119]
	v_mfma_f32_16x16x32_bf16 v[112:115], v[156:159], v[212:215], v[112:115]
	s_barrier
	v_add_u32_e32 v140, s56, v193
	v_add_u32_e32 v156, s57, v193
	ds_read_b128 v[128:131], v140
	ds_read_b128 v[132:135], v140 offset:1024
	ds_read_b128 v[136:139], v140 offset:2048
	ds_read_b128 v[140:143], v140 offset:3072
	ds_read_b128 v[144:147], v156
	ds_read_b128 v[148:151], v156 offset:1024
	ds_read_b128 v[152:155], v156 offset:2048
	ds_read_b128 v[156:159], v156 offset:3072
	s_add_u32 s0, s36, 0x2b0000
	s_addc_u32 s1, s37, 0
	s_mov_b32 m0, s46
	v_lshl_add_u64 v[224:225], s[0:1], 0, v[160:161]
	ds_read_b128 v[172:175], v196 offset:32768
	ds_read_b128 v[176:179], v196 offset:33792
	ds_read_b128 v[180:183], v196 offset:34816
	ds_read_b128 v[184:187], v196 offset:35840
	ds_read_b128 v[200:203], v196 offset:36864
	ds_read_b128 v[204:207], v196 offset:37888
	ds_read_b128 v[208:211], v196 offset:38912
	ds_read_b128 v[212:215], v196 offset:39936
	global_load_lds_dwordx4 v[224:225], off
	v_lshl_add_u64 v[224:225], s[0:1], 0, v[164:165]
	s_mov_b32 m0, s47
	s_nop 0
	global_load_lds_dwordx4 v[224:225], off
	s_waitcnt vmcnt(8)
	s_waitcnt lgkmcnt(0)
	s_barrier
	s_waitcnt lgkmcnt(0)
	v_mfma_f32_16x16x32_bf16 v[12:15], v[128:131], v[172:175], v[12:15]
	v_mfma_f32_16x16x32_bf16 v[8:11], v[136:139], v[172:175], v[8:11]
	v_mfma_f32_16x16x32_bf16 v[36:39], v[128:131], v[180:183], v[36:39]
	v_mfma_f32_16x16x32_bf16 v[32:35], v[136:139], v[180:183], v[32:35]
	v_mfma_f32_16x16x32_bf16 v[44:47], v[128:131], v[200:203], v[44:47]
	v_mfma_f32_16x16x32_bf16 v[40:43], v[136:139], v[200:203], v[40:43]
	v_mfma_f32_16x16x32_bf16 v[64:67], v[128:131], v[208:211], v[64:67]
	v_mfma_f32_16x16x32_bf16 v[56:59], v[136:139], v[208:211], v[56:59]
	v_mfma_f32_16x16x32_bf16 v[12:15], v[132:135], v[176:179], v[12:15]
	v_mfma_f32_16x16x32_bf16 v[8:11], v[140:143], v[176:179], v[8:11]
	v_mfma_f32_16x16x32_bf16 v[36:39], v[132:135], v[184:187], v[36:39]
	v_mfma_f32_16x16x32_bf16 v[32:35], v[140:143], v[184:187], v[32:35]
	v_mfma_f32_16x16x32_bf16 v[44:47], v[132:135], v[204:207], v[44:47]
	v_mfma_f32_16x16x32_bf16 v[40:43], v[140:143], v[204:207], v[40:43]
	v_mfma_f32_16x16x32_bf16 v[64:67], v[132:135], v[212:215], v[64:67]
	v_mfma_f32_16x16x32_bf16 v[56:59], v[140:143], v[212:215], v[56:59]
	v_mfma_f32_16x16x32_bf16 v[4:7], v[144:147], v[172:175], v[4:7]
	v_mfma_f32_16x16x32_bf16 v[0:3], v[152:155], v[172:175], v[0:3]
	v_mfma_f32_16x16x32_bf16 v[24:27], v[144:147], v[180:183], v[24:27]
	v_mfma_f32_16x16x32_bf16 v[16:19], v[152:155], v[180:183], v[16:19]
	v_mfma_f32_16x16x32_bf16 v[28:31], v[144:147], v[200:203], v[28:31]
	v_mfma_f32_16x16x32_bf16 v[20:23], v[152:155], v[200:203], v[20:23]
	v_mfma_f32_16x16x32_bf16 v[52:55], v[144:147], v[208:211], v[52:55]
	v_mfma_f32_16x16x32_bf16 v[48:51], v[152:155], v[208:211], v[48:51]
	v_mfma_f32_16x16x32_bf16 v[4:7], v[148:151], v[176:179], v[4:7]
	v_mfma_f32_16x16x32_bf16 v[0:3], v[156:159], v[176:179], v[0:3]
	v_mfma_f32_16x16x32_bf16 v[24:27], v[148:151], v[184:187], v[24:27]
	v_mfma_f32_16x16x32_bf16 v[16:19], v[156:159], v[184:187], v[16:19]
	v_mfma_f32_16x16x32_bf16 v[28:31], v[148:151], v[204:207], v[28:31]
	v_mfma_f32_16x16x32_bf16 v[20:23], v[156:159], v[204:207], v[20:23]
	v_mfma_f32_16x16x32_bf16 v[52:55], v[148:151], v[212:215], v[52:55]
	v_mfma_f32_16x16x32_bf16 v[48:51], v[156:159], v[212:215], v[48:51]
	s_barrier
	s_add_i32 s0, s56, s25
	v_lshl_add_u64 v[188:189], v[188:189], 0, s[18:19]
	s_mov_b32 m0, s0
	ds_read_b128 v[172:175], v196 offset:49152
	ds_read_b128 v[176:179], v196 offset:50176
	ds_read_b128 v[180:183], v196 offset:51200
	ds_read_b128 v[184:187], v196 offset:52224
	ds_read_b128 v[200:203], v196 offset:53248
	ds_read_b128 v[204:207], v196 offset:54272
	ds_read_b128 v[208:211], v196 offset:55296
	ds_read_b128 v[212:215], v196 offset:56320
	global_load_lds_dwordx4 v[188:189], off
	s_add_i32 m0, s0, 0x2000
	s_add_u32 s0, s4, 0x2b0080
	v_lshl_add_u64 v[188:189], v[216:217], 0, s[18:19]
	s_addc_u32 s1, s5, 0
	s_add_i32 s4, s57, s25
	global_load_lds_dwordx4 v[188:189], off
	v_lshl_add_u64 v[188:189], s[0:1], 0, v[162:163]
	s_mov_b32 m0, s4
	s_nop 0
	global_load_lds_dwordx4 v[188:189], off
	v_lshl_add_u64 v[188:189], s[0:1], 0, v[166:167]
	s_add_i32 m0, s4, 0x2000
	s_nop 0
	global_load_lds_dwordx4 v[188:189], off
	v_lshl_add_u64 v[188:189], v[220:221], 0, s[18:19]
	s_mov_b32 m0, s52
	s_nop 0
	global_load_lds_dwordx4 v[188:189], off
	v_lshl_add_u64 v[188:189], v[222:223], 0, s[18:19]
	s_mov_b32 m0, s53
	s_nop 0
	global_load_lds_dwordx4 v[188:189], off
	s_waitcnt vmcnt(8)
	s_waitcnt lgkmcnt(0)
	s_barrier
	s_waitcnt lgkmcnt(0)
	v_mfma_f32_16x16x32_bf16 v[76:79], v[128:131], v[172:175], v[76:79]
	v_mfma_f32_16x16x32_bf16 v[72:75], v[136:139], v[172:175], v[72:75]
	v_mfma_f32_16x16x32_bf16 v[92:95], v[128:131], v[180:183], v[92:95]
	v_mfma_f32_16x16x32_bf16 v[88:91], v[136:139], v[180:183], v[88:91]
	v_mfma_f32_16x16x32_bf16 v[108:111], v[128:131], v[200:203], v[108:111]
	v_mfma_f32_16x16x32_bf16 v[104:107], v[136:139], v[200:203], v[104:107]
	v_mfma_f32_16x16x32_bf16 v[124:127], v[128:131], v[208:211], v[124:127]
	v_mfma_f32_16x16x32_bf16 v[120:123], v[136:139], v[208:211], v[120:123]
	v_mfma_f32_16x16x32_bf16 v[76:79], v[132:135], v[176:179], v[76:79]
	v_mfma_f32_16x16x32_bf16 v[72:75], v[140:143], v[176:179], v[72:75]
	v_mfma_f32_16x16x32_bf16 v[92:95], v[132:135], v[184:187], v[92:95]
	v_mfma_f32_16x16x32_bf16 v[88:91], v[140:143], v[184:187], v[88:91]
	v_mfma_f32_16x16x32_bf16 v[108:111], v[132:135], v[204:207], v[108:111]
	v_mfma_f32_16x16x32_bf16 v[104:107], v[140:143], v[204:207], v[104:107]
	v_mfma_f32_16x16x32_bf16 v[124:127], v[132:135], v[212:215], v[124:127]
	v_mfma_f32_16x16x32_bf16 v[120:123], v[140:143], v[212:215], v[120:123]
	v_mfma_f32_16x16x32_bf16 v[68:71], v[144:147], v[172:175], v[68:71]
	v_mfma_f32_16x16x32_bf16 v[60:63], v[152:155], v[172:175], v[60:63]
	v_mfma_f32_16x16x32_bf16 v[84:87], v[144:147], v[180:183], v[84:87]
	v_mfma_f32_16x16x32_bf16 v[80:83], v[152:155], v[180:183], v[80:83]
	v_mfma_f32_16x16x32_bf16 v[100:103], v[144:147], v[200:203], v[100:103]
	v_mfma_f32_16x16x32_bf16 v[96:99], v[152:155], v[200:203], v[96:99]
	v_mfma_f32_16x16x32_bf16 v[116:119], v[144:147], v[208:211], v[116:119]
	v_mfma_f32_16x16x32_bf16 v[112:115], v[152:155], v[208:211], v[112:115]
	v_mfma_f32_16x16x32_bf16 v[68:71], v[148:151], v[176:179], v[68:71]
	v_mfma_f32_16x16x32_bf16 v[60:63], v[156:159], v[176:179], v[60:63]
	v_mfma_f32_16x16x32_bf16 v[84:87], v[148:151], v[184:187], v[84:87]
	v_mfma_f32_16x16x32_bf16 v[80:83], v[156:159], v[184:187], v[80:83]
	v_mfma_f32_16x16x32_bf16 v[100:103], v[148:151], v[204:207], v[100:103]
	v_mfma_f32_16x16x32_bf16 v[96:99], v[156:159], v[204:207], v[96:99]
	v_mfma_f32_16x16x32_bf16 v[116:119], v[148:151], v[212:215], v[116:119]
	v_mfma_f32_16x16x32_bf16 v[112:115], v[156:159], v[212:215], v[112:115]
	s_add_i32 s39, s39, 2
	s_add_u32 s29, s29, 0x100
	s_addc_u32 s38, s38, 0
	s_cmpk_gt_u32 s39, 0xa9
	s_mov_b64 s[0:1], s[2:3]
	s_barrier
	s_cbranch_scc0 .LBB0_1058
	s_and_b64 vcc, exec, s[20:21]
	s_cbranch_vccz .LBB0_1061
	s_barrier
